# final norm: lower-half rows held in registers across the mid barrier (no scratch copy), loads issued 4 rows ahead; original loops kept for other grid sizes
# speedup vs baseline: 1.0068x; 1.0068x over previous
; __device__ __forceinline__ int otid(int wv) { int t; asm volatile("v_mbcnt_lo_u32_b32 %0, -1, 0\n\tv_mbcnt_hi_u32_b32 %0, -1, %0\n\tv_lshl_add_u32 %0, %1, 6, %0" : "=&v"(t) : "s"(wv)); return t; }
; __global__ void __launch_bounds__(NTHR, 2) mega(Params p) {
;     ...
;     { const u64* ssF = (const u64*)(p.ws + WS_SS) + (size_t)8 * MTOK; const int tid = otid(wv);
;         const bf16_t* xh = (const bf16_t*)p.out; bf16_t* xcp = (bf16_t*)(p.ws + WS_BIG1);
;         for (size_t idx = (size_t)bid * NTHR + tid; idx < (size_t)16384 * DM / 8; idx += (size_t)G * NTHR) { const int r = 16384 + (int)(idx >> 7), c = (int)(idx & 127) * 8;
;             const u32x4 q = *(const u32x4*)(xh + (size_t)r * DM + c); const u32x4 q2 = *(const u32x4*)(xh + (size_t)(r - 16384) * DM + c);
;             *(u32x4*)(xcp + (size_t)(r - 16384) * DM + c) = q2;
;             const float rs = 1.0f / sqrtf((float)ssF[r] * SSKI + EPSN); const f32x4 g0 = *(const f32x4*)(p.g_final + c), g1 = *(const f32x4*)(p.g_final + c + 4);
.LBB0_797:
	s_cmpk_lg_u32 s34, 0x100
	s_cbranch_scc1 .Lfin_origA
	v_mbcnt_lo_u32_b32 v35, -1, 0
	v_mbcnt_hi_u32_b32 v35, -1, v35
	v_lshl_add_u32 v35, s33, 6, v35
	v_lshrrev_b32_e32 v34, 7, v35
	v_and_b32_e32 v35, 0x7f, v35
	v_lshlrev_b32_e32 v32, 11, v34
	v_lshl_add_u32 v32, v35, 4, v32
	v_lshlrev_b32_e32 v33, 12, v34
	v_lshl_add_u32 v33, v35, 5, v33
	v_lshlrev_b32_e32 v34, 3, v34
	v_lshlrev_b32_e32 v35, 5, v35
	v_mov_b32_e32 v200, 0x358637bd
	v_mov_b32_e32 v201, 0x260
	v_mov_b32_e32 v203, 0
	s_mov_b32 s63, 0xf800000
	s_lshl_b32 s36, s2, 13
	s_add_u32 s36, s28, s36
	s_addc_u32 s37, s29, 0
	s_add_u32 s38, s36, 0x2000000
	s_addc_u32 s39, s37, 0
	s_lshl_b32 s40, s2, 14
	s_add_u32 s40, s28, s40
	s_addc_u32 s41, s29, 0
	s_add_u32 s42, s40, 0x4000000
	s_addc_u32 s43, s41, 0
	s_add_u32 s44, s30, 0x200000
	s_addc_u32 s45, s31, 0
	s_lshl_b32 s46, s2, 5
	s_add_u32 s44, s44, s46
	s_addc_u32 s45, s45, 0
	s_add_u32 s46, s44, 0x20000
	s_addc_u32 s47, s45, 0
	global_load_dwordx4 v[36:39], v35, s[26:27]
	global_load_dwordx4 v[40:43], v35, s[26:27] offset:16
	global_load_dwordx4 v[64:67], v32, s[36:37]
	global_load_dwordx2 v[128:129], v34, s[44:45]
	s_add_u32 s36, s36, 0x200000
	s_addc_u32 s37, s37, 0
	s_add_u32 s44, s44, 0x2000
	s_addc_u32 s45, s45, 0
	global_load_dwordx4 v[68:71], v32, s[36:37]
	global_load_dwordx2 v[130:131], v34, s[44:45]
	s_add_u32 s36, s36, 0x200000
	s_addc_u32 s37, s37, 0
	s_add_u32 s44, s44, 0x2000
	s_addc_u32 s45, s45, 0
	global_load_dwordx4 v[72:75], v32, s[36:37]
	global_load_dwordx2 v[132:133], v34, s[44:45]
	s_add_u32 s36, s36, 0x200000
	s_addc_u32 s37, s37, 0
	s_add_u32 s44, s44, 0x2000
	s_addc_u32 s45, s45, 0
	global_load_dwordx4 v[76:79], v32, s[36:37]
	global_load_dwordx2 v[134:135], v34, s[44:45]
	s_add_u32 s36, s36, 0x200000
	s_addc_u32 s37, s37, 0
	s_add_u32 s44, s44, 0x2000
	s_addc_u32 s45, s45, 0
	global_load_dwordx4 v[80:83], v32, s[36:37]
	global_load_dwordx2 v[136:137], v34, s[44:45]
	s_add_u32 s36, s36, 0x200000
	s_addc_u32 s37, s37, 0
	s_add_u32 s44, s44, 0x2000
	s_addc_u32 s45, s45, 0
	global_load_dwordx4 v[84:87], v32, s[36:37]
	global_load_dwordx2 v[138:139], v34, s[44:45]
	s_add_u32 s36, s36, 0x200000
	s_addc_u32 s37, s37, 0
	s_add_u32 s44, s44, 0x2000
	s_addc_u32 s45, s45, 0
	global_load_dwordx4 v[88:91], v32, s[36:37]
	global_load_dwordx2 v[140:141], v34, s[44:45]
	s_add_u32 s36, s36, 0x200000
	s_addc_u32 s37, s37, 0
	s_add_u32 s44, s44, 0x2000
	s_addc_u32 s45, s45, 0
	global_load_dwordx4 v[92:95], v32, s[36:37]
	global_load_dwordx2 v[142:143], v34, s[44:45]
	s_add_u32 s36, s36, 0x200000
	s_addc_u32 s37, s37, 0
	s_add_u32 s44, s44, 0x2000
	s_addc_u32 s45, s45, 0
	global_load_dwordx4 v[96:99], v32, s[36:37]
	global_load_dwordx2 v[144:145], v34, s[44:45]
	s_add_u32 s36, s36, 0x200000
	s_addc_u32 s37, s37, 0
	s_add_u32 s44, s44, 0x2000
	s_addc_u32 s45, s45, 0
	global_load_dwordx4 v[100:103], v32, s[36:37]
	global_load_dwordx2 v[146:147], v34, s[44:45]
	s_add_u32 s36, s36, 0x200000
	s_addc_u32 s37, s37, 0
	s_add_u32 s44, s44, 0x2000
	s_addc_u32 s45, s45, 0
	global_load_dwordx4 v[104:107], v32, s[36:37]
	global_load_dwordx2 v[148:149], v34, s[44:45]
	s_add_u32 s36, s36, 0x200000
	s_addc_u32 s37, s37, 0
	s_add_u32 s44, s44, 0x2000
	s_addc_u32 s45, s45, 0
	global_load_dwordx4 v[108:111], v32, s[36:37]
	global_load_dwordx2 v[150:151], v34, s[44:45]
	s_add_u32 s36, s36, 0x200000
	s_addc_u32 s37, s37, 0
	s_add_u32 s44, s44, 0x2000
	s_addc_u32 s45, s45, 0
	global_load_dwordx4 v[112:115], v32, s[36:37]
	global_load_dwordx2 v[152:153], v34, s[44:45]
	s_add_u32 s36, s36, 0x200000
	s_addc_u32 s37, s37, 0
	s_add_u32 s44, s44, 0x2000
	s_addc_u32 s45, s45, 0
	global_load_dwordx4 v[116:119], v32, s[36:37]
	global_load_dwordx2 v[154:155], v34, s[44:45]
	s_add_u32 s36, s36, 0x200000
	s_addc_u32 s37, s37, 0
	s_add_u32 s44, s44, 0x2000
	s_addc_u32 s45, s45, 0
	global_load_dwordx4 v[120:123], v32, s[36:37]
	global_load_dwordx2 v[156:157], v34, s[44:45]
	s_add_u32 s36, s36, 0x200000
	s_addc_u32 s37, s37, 0
	s_add_u32 s44, s44, 0x2000
	s_addc_u32 s45, s45, 0
	global_load_dwordx4 v[124:127], v32, s[36:37]
	global_load_dwordx2 v[158:159], v34, s[44:45]
	global_load_dwordx4 v[176:179], v32, s[38:39]
	global_load_dwordx2 v[192:193], v34, s[46:47]
	s_add_u32 s38, s38, 0x200000
	s_addc_u32 s39, s39, 0
	s_add_u32 s46, s46, 0x2000
	s_addc_u32 s47, s47, 0
	global_load_dwordx4 v[180:183], v32, s[38:39]
	global_load_dwordx2 v[194:195], v34, s[46:47]
	s_add_u32 s38, s38, 0x200000
	s_addc_u32 s39, s39, 0
	s_add_u32 s46, s46, 0x2000
	s_addc_u32 s47, s47, 0
	global_load_dwordx4 v[184:187], v32, s[38:39]
	global_load_dwordx2 v[196:197], v34, s[46:47]
	s_add_u32 s38, s38, 0x200000
	s_addc_u32 s39, s39, 0
	s_add_u32 s46, s46, 0x2000
	s_addc_u32 s47, s47, 0
	global_load_dwordx4 v[188:191], v32, s[38:39]
	global_load_dwordx2 v[198:199], v34, s[46:47]
	s_add_u32 s38, s38, 0x200000
	s_addc_u32 s39, s39, 0
	s_add_u32 s46, s46, 0x2000
	s_addc_u32 s47, s47, 0
	s_waitcnt vmcnt(6)
; __global__ void __launch_bounds__(NTHR, 2) mega(Params p) {
;     ...
;         for (size_t idx = (size_t)bid * NTHR + tid; idx < (size_t)16384 * DM / 8; idx += (size_t)G * NTHR) { const int r = 16384 + (int)(idx >> 7), c = (int)(idx & 127) * 8;
;             const u32x4 q = *(const u32x4*)(xh + (size_t)r * DM + c); const u32x4 q2 = *(const u32x4*)(xh + (size_t)(r - 16384) * DM + c);
;             *(u32x4*)(xcp + (size_t)(r - 16384) * DM + c) = q2;
;             const float rs = 1.0f / sqrtf((float)ssF[r] * SSKI + EPSN); const f32x4 g0 = *(const f32x4*)(p.g_final + c), g1 = *(const f32x4*)(p.g_final + c + 4);
;             f32x4 v0 = {__uint_as_float(q.x << 16), __uint_as_float(q.x & 0xffff0000u), __uint_as_float(q.y << 16), __uint_as_float(q.y & 0xffff0000u)};
;             f32x4 v1 = {__uint_as_float(q.z << 16), __uint_as_float(q.z & 0xffff0000u), __uint_as_float(q.w << 16), __uint_as_float(q.w & 0xffff0000u)};
;             *(f32x4*)(p.out + (size_t)r * DM + c) = v0 * rs * g0; *(f32x4*)(p.out + (size_t)r * DM + c + 4) = v1 * rs * g1; }
	v_ffbh_u32_e32 v212, v193
	v_min_u32_e32 v212, 32, v212
	v_lshlrev_b64 v[214:215], v212, v[192:193]
	v_min_u32_e32 v214, 1, v214
	v_or_b32_e32 v214, v215, v214
	v_cvt_f32_u32_e32 v214, v214
	v_sub_u32_e32 v212, 32, v212
	v_ldexp_f32 v220, v214, v212
	v_fmamk_f32 v220, v220, 0x30800000, v200
	v_mul_f32_e32 v213, 0x4f800000, v220
	v_cmp_gt_f32_e32 vcc, s63, v220
	s_nop 1
	v_cndmask_b32_e32 v220, v220, v213, vcc
	v_sqrt_f32_e32 v213, v220
	s_nop 0
	v_add_u32_e32 v216, -1, v213
	v_add_u32_e32 v217, 1, v213
	v_fma_f32 v218, -v216, v213, v220
	v_fma_f32 v219, -v217, v213, v220
	v_cmp_ge_f32_e64 s[60:61], 0, v218
	s_nop 1
	v_cndmask_b32_e64 v213, v213, v216, s[60:61]
	v_cmp_lt_f32_e64 s[60:61], 0, v219
	s_nop 1
	v_cndmask_b32_e64 v213, v213, v217, s[60:61]
	v_mul_f32_e32 v216, 0x37800000, v213
	v_cndmask_b32_e32 v213, v213, v216, vcc
	v_cmp_class_f32_e32 vcc, v220, v201
	s_nop 1
	v_cndmask_b32_e32 v220, v213, v220, vcc
	v_div_scale_f32 v216, s[60:61], v220, v220, 1.0
	v_rcp_f32_e32 v213, v216
	v_div_scale_f32 v217, vcc, 1.0, v220, 1.0
	v_fma_f32 v218, -v216, v213, 1.0
	v_fmac_f32_e32 v213, v218, v213
	v_mul_f32_e32 v218, v217, v213
	v_fma_f32 v219, -v216, v218, v217
	v_fmac_f32_e32 v218, v219, v213
	v_fma_f32 v216, -v216, v218, v217
	v_div_fmas_f32 v216, v216, v213, v218
	v_div_fixup_f32 v220, v216, v220, 1.0
	v_lshlrev_b32_e32 v204, 16, v176
	v_and_b32_e32 v205, 0xffff0000, v176
	v_lshlrev_b32_e32 v206, 16, v177
	v_and_b32_e32 v207, 0xffff0000, v177
	v_lshlrev_b32_e32 v208, 16, v178
	v_and_b32_e32 v209, 0xffff0000, v178
	v_lshlrev_b32_e32 v210, 16, v179
	v_and_b32_e32 v211, 0xffff0000, v179
	v_mov_b32_e32 v202, v220
	v_pk_mul_f32 v[204:205], v[202:203], v[204:205] op_sel_hi:[0,1]
	v_pk_mul_f32 v[206:207], v[202:203], v[206:207] op_sel_hi:[0,1]
	v_pk_mul_f32 v[208:209], v[202:203], v[208:209] op_sel_hi:[0,1]
	v_pk_mul_f32 v[210:211], v[202:203], v[210:211] op_sel_hi:[0,1]
	v_pk_mul_f32 v[204:205], v[36:37], v[204:205]
	v_pk_mul_f32 v[206:207], v[38:39], v[206:207]
	v_pk_mul_f32 v[208:209], v[40:41], v[208:209]
	v_pk_mul_f32 v[210:211], v[42:43], v[210:211]
	global_store_dwordx4 v33, v[204:207], s[42:43]
	global_store_dwordx4 v33, v[208:211], s[42:43] offset:16
	s_add_u32 s42, s42, 0x400000
	s_addc_u32 s43, s43, 0
	global_load_dwordx4 v[176:179], v32, s[38:39]
	global_load_dwordx2 v[192:193], v34, s[46:47]
	s_add_u32 s38, s38, 0x200000
	s_addc_u32 s39, s39, 0
	s_add_u32 s46, s46, 0x2000
	s_addc_u32 s47, s47, 0
	s_waitcnt vmcnt(8)
	v_ffbh_u32_e32 v212, v195
	v_min_u32_e32 v212, 32, v212
	v_lshlrev_b64 v[214:215], v212, v[194:195]
	v_min_u32_e32 v214, 1, v214
	v_or_b32_e32 v214, v215, v214
	v_cvt_f32_u32_e32 v214, v214
	v_sub_u32_e32 v212, 32, v212
	v_ldexp_f32 v220, v214, v212
	v_fmamk_f32 v220, v220, 0x30800000, v200
	v_mul_f32_e32 v213, 0x4f800000, v220
	v_cmp_gt_f32_e32 vcc, s63, v220
	s_nop 1
	v_cndmask_b32_e32 v220, v220, v213, vcc
	v_sqrt_f32_e32 v213, v220
	s_nop 0
	v_add_u32_e32 v216, -1, v213
	v_add_u32_e32 v217, 1, v213
	v_fma_f32 v218, -v216, v213, v220
	v_fma_f32 v219, -v217, v213, v220
	v_cmp_ge_f32_e64 s[60:61], 0, v218
	s_nop 1
	v_cndmask_b32_e64 v213, v213, v216, s[60:61]
	v_cmp_lt_f32_e64 s[60:61], 0, v219
	s_nop 1
	v_cndmask_b32_e64 v213, v213, v217, s[60:61]
	v_mul_f32_e32 v216, 0x37800000, v213
	v_cndmask_b32_e32 v213, v213, v216, vcc
	v_cmp_class_f32_e32 vcc, v220, v201
	s_nop 1
	v_cndmask_b32_e32 v220, v213, v220, vcc
	v_div_scale_f32 v216, s[60:61], v220, v220, 1.0
	v_rcp_f32_e32 v213, v216
	v_div_scale_f32 v217, vcc, 1.0, v220, 1.0
	v_fma_f32 v218, -v216, v213, 1.0
	v_fmac_f32_e32 v213, v218, v213
	v_mul_f32_e32 v218, v217, v213
	v_fma_f32 v219, -v216, v218, v217
	v_fmac_f32_e32 v218, v219, v213
	v_fma_f32 v216, -v216, v218, v217
	v_div_fmas_f32 v216, v216, v213, v218
	v_div_fixup_f32 v220, v216, v220, 1.0
	v_lshlrev_b32_e32 v204, 16, v180
	v_and_b32_e32 v205, 0xffff0000, v180
	v_lshlrev_b32_e32 v206, 16, v181
	v_and_b32_e32 v207, 0xffff0000, v181
	v_lshlrev_b32_e32 v208, 16, v182
	v_and_b32_e32 v209, 0xffff0000, v182
	v_lshlrev_b32_e32 v210, 16, v183
	v_and_b32_e32 v211, 0xffff0000, v183
	v_mov_b32_e32 v202, v220
	v_pk_mul_f32 v[204:205], v[202:203], v[204:205] op_sel_hi:[0,1]
	v_pk_mul_f32 v[206:207], v[202:203], v[206:207] op_sel_hi:[0,1]
	v_pk_mul_f32 v[208:209], v[202:203], v[208:209] op_sel_hi:[0,1]
	v_pk_mul_f32 v[210:211], v[202:203], v[210:211] op_sel_hi:[0,1]
	v_pk_mul_f32 v[204:205], v[36:37], v[204:205]
	v_pk_mul_f32 v[206:207], v[38:39], v[206:207]
	v_pk_mul_f32 v[208:209], v[40:41], v[208:209]
	v_pk_mul_f32 v[210:211], v[42:43], v[210:211]
	global_store_dwordx4 v33, v[204:207], s[42:43]
	global_store_dwordx4 v33, v[208:211], s[42:43] offset:16
	s_add_u32 s42, s42, 0x400000
	s_addc_u32 s43, s43, 0
	global_load_dwordx4 v[180:183], v32, s[38:39]
	global_load_dwordx2 v[194:195], v34, s[46:47]
	s_add_u32 s38, s38, 0x200000
	s_addc_u32 s39, s39, 0
	s_add_u32 s46, s46, 0x2000
	s_addc_u32 s47, s47, 0
	s_waitcnt vmcnt(10)
; __global__ void __launch_bounds__(NTHR, 2) mega(Params p) {
;     ...
;         for (size_t idx = (size_t)bid * NTHR + tid; idx < (size_t)16384 * DM / 8; idx += (size_t)G * NTHR) { const int r = 16384 + (int)(idx >> 7), c = (int)(idx & 127) * 8;
;             const u32x4 q = *(const u32x4*)(xh + (size_t)r * DM + c); const u32x4 q2 = *(const u32x4*)(xh + (size_t)(r - 16384) * DM + c);
;             *(u32x4*)(xcp + (size_t)(r - 16384) * DM + c) = q2;
;             const float rs = 1.0f / sqrtf((float)ssF[r] * SSKI + EPSN); const f32x4 g0 = *(const f32x4*)(p.g_final + c), g1 = *(const f32x4*)(p.g_final + c + 4);
;             f32x4 v0 = {__uint_as_float(q.x << 16), __uint_as_float(q.x & 0xffff0000u), __uint_as_float(q.y << 16), __uint_as_float(q.y & 0xffff0000u)};
;             f32x4 v1 = {__uint_as_float(q.z << 16), __uint_as_float(q.z & 0xffff0000u), __uint_as_float(q.w << 16), __uint_as_float(q.w & 0xffff0000u)};
;             *(f32x4*)(p.out + (size_t)r * DM + c) = v0 * rs * g0; *(f32x4*)(p.out + (size_t)r * DM + c + 4) = v1 * rs * g1; }
	v_ffbh_u32_e32 v212, v197
	v_min_u32_e32 v212, 32, v212
	v_lshlrev_b64 v[214:215], v212, v[196:197]
	v_min_u32_e32 v214, 1, v214
	v_or_b32_e32 v214, v215, v214
	v_cvt_f32_u32_e32 v214, v214
	v_sub_u32_e32 v212, 32, v212
	v_ldexp_f32 v220, v214, v212
	v_fmamk_f32 v220, v220, 0x30800000, v200
	v_mul_f32_e32 v213, 0x4f800000, v220
	v_cmp_gt_f32_e32 vcc, s63, v220
	s_nop 1
	v_cndmask_b32_e32 v220, v220, v213, vcc
	v_sqrt_f32_e32 v213, v220
	s_nop 0
	v_add_u32_e32 v216, -1, v213
	v_add_u32_e32 v217, 1, v213
	v_fma_f32 v218, -v216, v213, v220
	v_fma_f32 v219, -v217, v213, v220
	v_cmp_ge_f32_e64 s[60:61], 0, v218
	s_nop 1
	v_cndmask_b32_e64 v213, v213, v216, s[60:61]
	v_cmp_lt_f32_e64 s[60:61], 0, v219
	s_nop 1
	v_cndmask_b32_e64 v213, v213, v217, s[60:61]
	v_mul_f32_e32 v216, 0x37800000, v213
	v_cndmask_b32_e32 v213, v213, v216, vcc
	v_cmp_class_f32_e32 vcc, v220, v201
	s_nop 1
	v_cndmask_b32_e32 v220, v213, v220, vcc
	v_div_scale_f32 v216, s[60:61], v220, v220, 1.0
	v_rcp_f32_e32 v213, v216
	v_div_scale_f32 v217, vcc, 1.0, v220, 1.0
	v_fma_f32 v218, -v216, v213, 1.0
	v_fmac_f32_e32 v213, v218, v213
	v_mul_f32_e32 v218, v217, v213
	v_fma_f32 v219, -v216, v218, v217
	v_fmac_f32_e32 v218, v219, v213
	v_fma_f32 v216, -v216, v218, v217
	v_div_fmas_f32 v216, v216, v213, v218
	v_div_fixup_f32 v220, v216, v220, 1.0
	v_lshlrev_b32_e32 v204, 16, v184
	v_and_b32_e32 v205, 0xffff0000, v184
	v_lshlrev_b32_e32 v206, 16, v185
	v_and_b32_e32 v207, 0xffff0000, v185
	v_lshlrev_b32_e32 v208, 16, v186
	v_and_b32_e32 v209, 0xffff0000, v186
	v_lshlrev_b32_e32 v210, 16, v187
	v_and_b32_e32 v211, 0xffff0000, v187
	v_mov_b32_e32 v202, v220
	v_pk_mul_f32 v[204:205], v[202:203], v[204:205] op_sel_hi:[0,1]
	v_pk_mul_f32 v[206:207], v[202:203], v[206:207] op_sel_hi:[0,1]
	v_pk_mul_f32 v[208:209], v[202:203], v[208:209] op_sel_hi:[0,1]
	v_pk_mul_f32 v[210:211], v[202:203], v[210:211] op_sel_hi:[0,1]
	v_pk_mul_f32 v[204:205], v[36:37], v[204:205]
	v_pk_mul_f32 v[206:207], v[38:39], v[206:207]
	v_pk_mul_f32 v[208:209], v[40:41], v[208:209]
	v_pk_mul_f32 v[210:211], v[42:43], v[210:211]
	global_store_dwordx4 v33, v[204:207], s[42:43]
	global_store_dwordx4 v33, v[208:211], s[42:43] offset:16
	s_add_u32 s42, s42, 0x400000
	s_addc_u32 s43, s43, 0
	global_load_dwordx4 v[184:187], v32, s[38:39]
	global_load_dwordx2 v[196:197], v34, s[46:47]
	s_add_u32 s38, s38, 0x200000
	s_addc_u32 s39, s39, 0
	s_add_u32 s46, s46, 0x2000
	s_addc_u32 s47, s47, 0
	s_waitcnt vmcnt(12)
	v_ffbh_u32_e32 v212, v199
	v_min_u32_e32 v212, 32, v212
	v_lshlrev_b64 v[214:215], v212, v[198:199]
	v_min_u32_e32 v214, 1, v214
	v_or_b32_e32 v214, v215, v214
	v_cvt_f32_u32_e32 v214, v214
	v_sub_u32_e32 v212, 32, v212
	v_ldexp_f32 v220, v214, v212
	v_fmamk_f32 v220, v220, 0x30800000, v200
	v_mul_f32_e32 v213, 0x4f800000, v220
	v_cmp_gt_f32_e32 vcc, s63, v220
	s_nop 1
	v_cndmask_b32_e32 v220, v220, v213, vcc
	v_sqrt_f32_e32 v213, v220
	s_nop 0
	v_add_u32_e32 v216, -1, v213
	v_add_u32_e32 v217, 1, v213
	v_fma_f32 v218, -v216, v213, v220
	v_fma_f32 v219, -v217, v213, v220
	v_cmp_ge_f32_e64 s[60:61], 0, v218
	s_nop 1
	v_cndmask_b32_e64 v213, v213, v216, s[60:61]
	v_cmp_lt_f32_e64 s[60:61], 0, v219
	s_nop 1
	v_cndmask_b32_e64 v213, v213, v217, s[60:61]
	v_mul_f32_e32 v216, 0x37800000, v213
	v_cndmask_b32_e32 v213, v213, v216, vcc
	v_cmp_class_f32_e32 vcc, v220, v201
	s_nop 1
	v_cndmask_b32_e32 v220, v213, v220, vcc
	v_div_scale_f32 v216, s[60:61], v220, v220, 1.0
	v_rcp_f32_e32 v213, v216
	v_div_scale_f32 v217, vcc, 1.0, v220, 1.0
	v_fma_f32 v218, -v216, v213, 1.0
	v_fmac_f32_e32 v213, v218, v213
	v_mul_f32_e32 v218, v217, v213
	v_fma_f32 v219, -v216, v218, v217
	v_fmac_f32_e32 v218, v219, v213
	v_fma_f32 v216, -v216, v218, v217
	v_div_fmas_f32 v216, v216, v213, v218
	v_div_fixup_f32 v220, v216, v220, 1.0
	v_lshlrev_b32_e32 v204, 16, v188
	v_and_b32_e32 v205, 0xffff0000, v188
	v_lshlrev_b32_e32 v206, 16, v189
	v_and_b32_e32 v207, 0xffff0000, v189
	v_lshlrev_b32_e32 v208, 16, v190
	v_and_b32_e32 v209, 0xffff0000, v190
	v_lshlrev_b32_e32 v210, 16, v191
	v_and_b32_e32 v211, 0xffff0000, v191
	v_mov_b32_e32 v202, v220
	v_pk_mul_f32 v[204:205], v[202:203], v[204:205] op_sel_hi:[0,1]
	v_pk_mul_f32 v[206:207], v[202:203], v[206:207] op_sel_hi:[0,1]
	v_pk_mul_f32 v[208:209], v[202:203], v[208:209] op_sel_hi:[0,1]
	v_pk_mul_f32 v[210:211], v[202:203], v[210:211] op_sel_hi:[0,1]
	v_pk_mul_f32 v[204:205], v[36:37], v[204:205]
	v_pk_mul_f32 v[206:207], v[38:39], v[206:207]
	v_pk_mul_f32 v[208:209], v[40:41], v[208:209]
	v_pk_mul_f32 v[210:211], v[42:43], v[210:211]
	global_store_dwordx4 v33, v[204:207], s[42:43]
	global_store_dwordx4 v33, v[208:211], s[42:43] offset:16
	s_add_u32 s42, s42, 0x400000
	s_addc_u32 s43, s43, 0
	global_load_dwordx4 v[188:191], v32, s[38:39]
	global_load_dwordx2 v[198:199], v34, s[46:47]
	s_add_u32 s38, s38, 0x200000
	s_addc_u32 s39, s39, 0
	s_add_u32 s46, s46, 0x2000
	s_addc_u32 s47, s47, 0
	s_waitcnt vmcnt(12)
; __global__ void __launch_bounds__(NTHR, 2) mega(Params p) {
;     ...
;         for (size_t idx = (size_t)bid * NTHR + tid; idx < (size_t)16384 * DM / 8; idx += (size_t)G * NTHR) { const int r = 16384 + (int)(idx >> 7), c = (int)(idx & 127) * 8;
;             const u32x4 q = *(const u32x4*)(xh + (size_t)r * DM + c); const u32x4 q2 = *(const u32x4*)(xh + (size_t)(r - 16384) * DM + c);
;             *(u32x4*)(xcp + (size_t)(r - 16384) * DM + c) = q2;
;             const float rs = 1.0f / sqrtf((float)ssF[r] * SSKI + EPSN); const f32x4 g0 = *(const f32x4*)(p.g_final + c), g1 = *(const f32x4*)(p.g_final + c + 4);
;             f32x4 v0 = {__uint_as_float(q.x << 16), __uint_as_float(q.x & 0xffff0000u), __uint_as_float(q.y << 16), __uint_as_float(q.y & 0xffff0000u)};
;             f32x4 v1 = {__uint_as_float(q.z << 16), __uint_as_float(q.z & 0xffff0000u), __uint_as_float(q.w << 16), __uint_as_float(q.w & 0xffff0000u)};
;             *(f32x4*)(p.out + (size_t)r * DM + c) = v0 * rs * g0; *(f32x4*)(p.out + (size_t)r * DM + c + 4) = v1 * rs * g1; }
	v_ffbh_u32_e32 v212, v193
	v_min_u32_e32 v212, 32, v212
	v_lshlrev_b64 v[214:215], v212, v[192:193]
	v_min_u32_e32 v214, 1, v214
	v_or_b32_e32 v214, v215, v214
	v_cvt_f32_u32_e32 v214, v214
	v_sub_u32_e32 v212, 32, v212
	v_ldexp_f32 v220, v214, v212
	v_fmamk_f32 v220, v220, 0x30800000, v200
	v_mul_f32_e32 v213, 0x4f800000, v220
	v_cmp_gt_f32_e32 vcc, s63, v220
	s_nop 1
	v_cndmask_b32_e32 v220, v220, v213, vcc
	v_sqrt_f32_e32 v213, v220
	s_nop 0
	v_add_u32_e32 v216, -1, v213
	v_add_u32_e32 v217, 1, v213
	v_fma_f32 v218, -v216, v213, v220
	v_fma_f32 v219, -v217, v213, v220
	v_cmp_ge_f32_e64 s[60:61], 0, v218
	s_nop 1
	v_cndmask_b32_e64 v213, v213, v216, s[60:61]
	v_cmp_lt_f32_e64 s[60:61], 0, v219
	s_nop 1
	v_cndmask_b32_e64 v213, v213, v217, s[60:61]
	v_mul_f32_e32 v216, 0x37800000, v213
	v_cndmask_b32_e32 v213, v213, v216, vcc
	v_cmp_class_f32_e32 vcc, v220, v201
	s_nop 1
	v_cndmask_b32_e32 v220, v213, v220, vcc
	v_div_scale_f32 v216, s[60:61], v220, v220, 1.0
	v_rcp_f32_e32 v213, v216
	v_div_scale_f32 v217, vcc, 1.0, v220, 1.0
	v_fma_f32 v218, -v216, v213, 1.0
	v_fmac_f32_e32 v213, v218, v213
	v_mul_f32_e32 v218, v217, v213
	v_fma_f32 v219, -v216, v218, v217
	v_fmac_f32_e32 v218, v219, v213
	v_fma_f32 v216, -v216, v218, v217
	v_div_fmas_f32 v216, v216, v213, v218
	v_div_fixup_f32 v220, v216, v220, 1.0
	v_lshlrev_b32_e32 v204, 16, v176
	v_and_b32_e32 v205, 0xffff0000, v176
	v_lshlrev_b32_e32 v206, 16, v177
	v_and_b32_e32 v207, 0xffff0000, v177
	v_lshlrev_b32_e32 v208, 16, v178
	v_and_b32_e32 v209, 0xffff0000, v178
	v_lshlrev_b32_e32 v210, 16, v179
	v_and_b32_e32 v211, 0xffff0000, v179
	v_mov_b32_e32 v202, v220
	v_pk_mul_f32 v[204:205], v[202:203], v[204:205] op_sel_hi:[0,1]
	v_pk_mul_f32 v[206:207], v[202:203], v[206:207] op_sel_hi:[0,1]
	v_pk_mul_f32 v[208:209], v[202:203], v[208:209] op_sel_hi:[0,1]
	v_pk_mul_f32 v[210:211], v[202:203], v[210:211] op_sel_hi:[0,1]
	v_pk_mul_f32 v[204:205], v[36:37], v[204:205]
	v_pk_mul_f32 v[206:207], v[38:39], v[206:207]
	v_pk_mul_f32 v[208:209], v[40:41], v[208:209]
	v_pk_mul_f32 v[210:211], v[42:43], v[210:211]
	global_store_dwordx4 v33, v[204:207], s[42:43]
	global_store_dwordx4 v33, v[208:211], s[42:43] offset:16
	s_add_u32 s42, s42, 0x400000
	s_addc_u32 s43, s43, 0
	global_load_dwordx4 v[176:179], v32, s[38:39]
	global_load_dwordx2 v[192:193], v34, s[46:47]
	s_add_u32 s38, s38, 0x200000
	s_addc_u32 s39, s39, 0
	s_add_u32 s46, s46, 0x2000
	s_addc_u32 s47, s47, 0
	s_waitcnt vmcnt(12)
	v_ffbh_u32_e32 v212, v195
	v_min_u32_e32 v212, 32, v212
	v_lshlrev_b64 v[214:215], v212, v[194:195]
	v_min_u32_e32 v214, 1, v214
	v_or_b32_e32 v214, v215, v214
	v_cvt_f32_u32_e32 v214, v214
	v_sub_u32_e32 v212, 32, v212
	v_ldexp_f32 v220, v214, v212
	v_fmamk_f32 v220, v220, 0x30800000, v200
	v_mul_f32_e32 v213, 0x4f800000, v220
	v_cmp_gt_f32_e32 vcc, s63, v220
	s_nop 1
	v_cndmask_b32_e32 v220, v220, v213, vcc
	v_sqrt_f32_e32 v213, v220
	s_nop 0
	v_add_u32_e32 v216, -1, v213
	v_add_u32_e32 v217, 1, v213
	v_fma_f32 v218, -v216, v213, v220
	v_fma_f32 v219, -v217, v213, v220
	v_cmp_ge_f32_e64 s[60:61], 0, v218
	s_nop 1
	v_cndmask_b32_e64 v213, v213, v216, s[60:61]
	v_cmp_lt_f32_e64 s[60:61], 0, v219
	s_nop 1
	v_cndmask_b32_e64 v213, v213, v217, s[60:61]
	v_mul_f32_e32 v216, 0x37800000, v213
	v_cndmask_b32_e32 v213, v213, v216, vcc
	v_cmp_class_f32_e32 vcc, v220, v201
	s_nop 1
	v_cndmask_b32_e32 v220, v213, v220, vcc
	v_div_scale_f32 v216, s[60:61], v220, v220, 1.0
	v_rcp_f32_e32 v213, v216
	v_div_scale_f32 v217, vcc, 1.0, v220, 1.0
	v_fma_f32 v218, -v216, v213, 1.0
	v_fmac_f32_e32 v213, v218, v213
	v_mul_f32_e32 v218, v217, v213
	v_fma_f32 v219, -v216, v218, v217
	v_fmac_f32_e32 v218, v219, v213
	v_fma_f32 v216, -v216, v218, v217
	v_div_fmas_f32 v216, v216, v213, v218
	v_div_fixup_f32 v220, v216, v220, 1.0
	v_lshlrev_b32_e32 v204, 16, v180
	v_and_b32_e32 v205, 0xffff0000, v180
	v_lshlrev_b32_e32 v206, 16, v181
	v_and_b32_e32 v207, 0xffff0000, v181
	v_lshlrev_b32_e32 v208, 16, v182
	v_and_b32_e32 v209, 0xffff0000, v182
	v_lshlrev_b32_e32 v210, 16, v183
	v_and_b32_e32 v211, 0xffff0000, v183
	v_mov_b32_e32 v202, v220
	v_pk_mul_f32 v[204:205], v[202:203], v[204:205] op_sel_hi:[0,1]
	v_pk_mul_f32 v[206:207], v[202:203], v[206:207] op_sel_hi:[0,1]
	v_pk_mul_f32 v[208:209], v[202:203], v[208:209] op_sel_hi:[0,1]
	v_pk_mul_f32 v[210:211], v[202:203], v[210:211] op_sel_hi:[0,1]
	v_pk_mul_f32 v[204:205], v[36:37], v[204:205]
	v_pk_mul_f32 v[206:207], v[38:39], v[206:207]
	v_pk_mul_f32 v[208:209], v[40:41], v[208:209]
	v_pk_mul_f32 v[210:211], v[42:43], v[210:211]
	global_store_dwordx4 v33, v[204:207], s[42:43]
	global_store_dwordx4 v33, v[208:211], s[42:43] offset:16
	s_add_u32 s42, s42, 0x400000
	s_addc_u32 s43, s43, 0
	global_load_dwordx4 v[180:183], v32, s[38:39]
	global_load_dwordx2 v[194:195], v34, s[46:47]
	s_add_u32 s38, s38, 0x200000
	s_addc_u32 s39, s39, 0
	s_add_u32 s46, s46, 0x2000
	s_addc_u32 s47, s47, 0
	s_waitcnt vmcnt(12)
; __global__ void __launch_bounds__(NTHR, 2) mega(Params p) {
;     ...
;         for (size_t idx = (size_t)bid * NTHR + tid; idx < (size_t)16384 * DM / 8; idx += (size_t)G * NTHR) { const int r = 16384 + (int)(idx >> 7), c = (int)(idx & 127) * 8;
;             const u32x4 q = *(const u32x4*)(xh + (size_t)r * DM + c); const u32x4 q2 = *(const u32x4*)(xh + (size_t)(r - 16384) * DM + c);
;             *(u32x4*)(xcp + (size_t)(r - 16384) * DM + c) = q2;
;             const float rs = 1.0f / sqrtf((float)ssF[r] * SSKI + EPSN); const f32x4 g0 = *(const f32x4*)(p.g_final + c), g1 = *(const f32x4*)(p.g_final + c + 4);
;             f32x4 v0 = {__uint_as_float(q.x << 16), __uint_as_float(q.x & 0xffff0000u), __uint_as_float(q.y << 16), __uint_as_float(q.y & 0xffff0000u)};
;             f32x4 v1 = {__uint_as_float(q.z << 16), __uint_as_float(q.z & 0xffff0000u), __uint_as_float(q.w << 16), __uint_as_float(q.w & 0xffff0000u)};
;             *(f32x4*)(p.out + (size_t)r * DM + c) = v0 * rs * g0; *(f32x4*)(p.out + (size_t)r * DM + c + 4) = v1 * rs * g1; }
	v_ffbh_u32_e32 v212, v197
	v_min_u32_e32 v212, 32, v212
	v_lshlrev_b64 v[214:215], v212, v[196:197]
	v_min_u32_e32 v214, 1, v214
	v_or_b32_e32 v214, v215, v214
	v_cvt_f32_u32_e32 v214, v214
	v_sub_u32_e32 v212, 32, v212
	v_ldexp_f32 v220, v214, v212
	v_fmamk_f32 v220, v220, 0x30800000, v200
	v_mul_f32_e32 v213, 0x4f800000, v220
	v_cmp_gt_f32_e32 vcc, s63, v220
	s_nop 1
	v_cndmask_b32_e32 v220, v220, v213, vcc
	v_sqrt_f32_e32 v213, v220
	s_nop 0
	v_add_u32_e32 v216, -1, v213
	v_add_u32_e32 v217, 1, v213
	v_fma_f32 v218, -v216, v213, v220
	v_fma_f32 v219, -v217, v213, v220
	v_cmp_ge_f32_e64 s[60:61], 0, v218
	s_nop 1
	v_cndmask_b32_e64 v213, v213, v216, s[60:61]
	v_cmp_lt_f32_e64 s[60:61], 0, v219
	s_nop 1
	v_cndmask_b32_e64 v213, v213, v217, s[60:61]
	v_mul_f32_e32 v216, 0x37800000, v213
	v_cndmask_b32_e32 v213, v213, v216, vcc
	v_cmp_class_f32_e32 vcc, v220, v201
	s_nop 1
	v_cndmask_b32_e32 v220, v213, v220, vcc
	v_div_scale_f32 v216, s[60:61], v220, v220, 1.0
	v_rcp_f32_e32 v213, v216
	v_div_scale_f32 v217, vcc, 1.0, v220, 1.0
	v_fma_f32 v218, -v216, v213, 1.0
	v_fmac_f32_e32 v213, v218, v213
	v_mul_f32_e32 v218, v217, v213
	v_fma_f32 v219, -v216, v218, v217
	v_fmac_f32_e32 v218, v219, v213
	v_fma_f32 v216, -v216, v218, v217
	v_div_fmas_f32 v216, v216, v213, v218
	v_div_fixup_f32 v220, v216, v220, 1.0
	v_lshlrev_b32_e32 v204, 16, v184
	v_and_b32_e32 v205, 0xffff0000, v184
	v_lshlrev_b32_e32 v206, 16, v185
	v_and_b32_e32 v207, 0xffff0000, v185
	v_lshlrev_b32_e32 v208, 16, v186
	v_and_b32_e32 v209, 0xffff0000, v186
	v_lshlrev_b32_e32 v210, 16, v187
	v_and_b32_e32 v211, 0xffff0000, v187
	v_mov_b32_e32 v202, v220
	v_pk_mul_f32 v[204:205], v[202:203], v[204:205] op_sel_hi:[0,1]
	v_pk_mul_f32 v[206:207], v[202:203], v[206:207] op_sel_hi:[0,1]
	v_pk_mul_f32 v[208:209], v[202:203], v[208:209] op_sel_hi:[0,1]
	v_pk_mul_f32 v[210:211], v[202:203], v[210:211] op_sel_hi:[0,1]
	v_pk_mul_f32 v[204:205], v[36:37], v[204:205]
	v_pk_mul_f32 v[206:207], v[38:39], v[206:207]
	v_pk_mul_f32 v[208:209], v[40:41], v[208:209]
	v_pk_mul_f32 v[210:211], v[42:43], v[210:211]
	global_store_dwordx4 v33, v[204:207], s[42:43]
	global_store_dwordx4 v33, v[208:211], s[42:43] offset:16
	s_add_u32 s42, s42, 0x400000
	s_addc_u32 s43, s43, 0
	global_load_dwordx4 v[184:187], v32, s[38:39]
	global_load_dwordx2 v[196:197], v34, s[46:47]
	s_add_u32 s38, s38, 0x200000
	s_addc_u32 s39, s39, 0
	s_add_u32 s46, s46, 0x2000
	s_addc_u32 s47, s47, 0
	s_waitcnt vmcnt(12)
	v_ffbh_u32_e32 v212, v199
	v_min_u32_e32 v212, 32, v212
	v_lshlrev_b64 v[214:215], v212, v[198:199]
	v_min_u32_e32 v214, 1, v214
	v_or_b32_e32 v214, v215, v214
	v_cvt_f32_u32_e32 v214, v214
	v_sub_u32_e32 v212, 32, v212
	v_ldexp_f32 v220, v214, v212
	v_fmamk_f32 v220, v220, 0x30800000, v200
	v_mul_f32_e32 v213, 0x4f800000, v220
	v_cmp_gt_f32_e32 vcc, s63, v220
	s_nop 1
	v_cndmask_b32_e32 v220, v220, v213, vcc
	v_sqrt_f32_e32 v213, v220
	s_nop 0
	v_add_u32_e32 v216, -1, v213
	v_add_u32_e32 v217, 1, v213
	v_fma_f32 v218, -v216, v213, v220
	v_fma_f32 v219, -v217, v213, v220
	v_cmp_ge_f32_e64 s[60:61], 0, v218
	s_nop 1
	v_cndmask_b32_e64 v213, v213, v216, s[60:61]
	v_cmp_lt_f32_e64 s[60:61], 0, v219
	s_nop 1
	v_cndmask_b32_e64 v213, v213, v217, s[60:61]
	v_mul_f32_e32 v216, 0x37800000, v213
	v_cndmask_b32_e32 v213, v213, v216, vcc
	v_cmp_class_f32_e32 vcc, v220, v201
	s_nop 1
	v_cndmask_b32_e32 v220, v213, v220, vcc
	v_div_scale_f32 v216, s[60:61], v220, v220, 1.0
	v_rcp_f32_e32 v213, v216
	v_div_scale_f32 v217, vcc, 1.0, v220, 1.0
	v_fma_f32 v218, -v216, v213, 1.0
	v_fmac_f32_e32 v213, v218, v213
	v_mul_f32_e32 v218, v217, v213
	v_fma_f32 v219, -v216, v218, v217
	v_fmac_f32_e32 v218, v219, v213
	v_fma_f32 v216, -v216, v218, v217
	v_div_fmas_f32 v216, v216, v213, v218
	v_div_fixup_f32 v220, v216, v220, 1.0
	v_lshlrev_b32_e32 v204, 16, v188
	v_and_b32_e32 v205, 0xffff0000, v188
	v_lshlrev_b32_e32 v206, 16, v189
	v_and_b32_e32 v207, 0xffff0000, v189
	v_lshlrev_b32_e32 v208, 16, v190
	v_and_b32_e32 v209, 0xffff0000, v190
	v_lshlrev_b32_e32 v210, 16, v191
	v_and_b32_e32 v211, 0xffff0000, v191
	v_mov_b32_e32 v202, v220
	v_pk_mul_f32 v[204:205], v[202:203], v[204:205] op_sel_hi:[0,1]
	v_pk_mul_f32 v[206:207], v[202:203], v[206:207] op_sel_hi:[0,1]
	v_pk_mul_f32 v[208:209], v[202:203], v[208:209] op_sel_hi:[0,1]
	v_pk_mul_f32 v[210:211], v[202:203], v[210:211] op_sel_hi:[0,1]
	v_pk_mul_f32 v[204:205], v[36:37], v[204:205]
	v_pk_mul_f32 v[206:207], v[38:39], v[206:207]
	v_pk_mul_f32 v[208:209], v[40:41], v[208:209]
	v_pk_mul_f32 v[210:211], v[42:43], v[210:211]
	global_store_dwordx4 v33, v[204:207], s[42:43]
	global_store_dwordx4 v33, v[208:211], s[42:43] offset:16
	s_add_u32 s42, s42, 0x400000
	s_addc_u32 s43, s43, 0
	global_load_dwordx4 v[188:191], v32, s[38:39]
	global_load_dwordx2 v[198:199], v34, s[46:47]
	s_add_u32 s38, s38, 0x200000
	s_addc_u32 s39, s39, 0
	s_add_u32 s46, s46, 0x2000
	s_addc_u32 s47, s47, 0
	s_waitcnt vmcnt(12)
; __global__ void __launch_bounds__(NTHR, 2) mega(Params p) {
;     ...
;         for (size_t idx = (size_t)bid * NTHR + tid; idx < (size_t)16384 * DM / 8; idx += (size_t)G * NTHR) { const int r = 16384 + (int)(idx >> 7), c = (int)(idx & 127) * 8;
;             const u32x4 q = *(const u32x4*)(xh + (size_t)r * DM + c); const u32x4 q2 = *(const u32x4*)(xh + (size_t)(r - 16384) * DM + c);
;             *(u32x4*)(xcp + (size_t)(r - 16384) * DM + c) = q2;
;             const float rs = 1.0f / sqrtf((float)ssF[r] * SSKI + EPSN); const f32x4 g0 = *(const f32x4*)(p.g_final + c), g1 = *(const f32x4*)(p.g_final + c + 4);
;             f32x4 v0 = {__uint_as_float(q.x << 16), __uint_as_float(q.x & 0xffff0000u), __uint_as_float(q.y << 16), __uint_as_float(q.y & 0xffff0000u)};
;             f32x4 v1 = {__uint_as_float(q.z << 16), __uint_as_float(q.z & 0xffff0000u), __uint_as_float(q.w << 16), __uint_as_float(q.w & 0xffff0000u)};
;             *(f32x4*)(p.out + (size_t)r * DM + c) = v0 * rs * g0; *(f32x4*)(p.out + (size_t)r * DM + c + 4) = v1 * rs * g1; }
	v_ffbh_u32_e32 v212, v193
	v_min_u32_e32 v212, 32, v212
	v_lshlrev_b64 v[214:215], v212, v[192:193]
	v_min_u32_e32 v214, 1, v214
	v_or_b32_e32 v214, v215, v214
	v_cvt_f32_u32_e32 v214, v214
	v_sub_u32_e32 v212, 32, v212
	v_ldexp_f32 v220, v214, v212
	v_fmamk_f32 v220, v220, 0x30800000, v200
	v_mul_f32_e32 v213, 0x4f800000, v220
	v_cmp_gt_f32_e32 vcc, s63, v220
	s_nop 1
	v_cndmask_b32_e32 v220, v220, v213, vcc
	v_sqrt_f32_e32 v213, v220
	s_nop 0
	v_add_u32_e32 v216, -1, v213
	v_add_u32_e32 v217, 1, v213
	v_fma_f32 v218, -v216, v213, v220
	v_fma_f32 v219, -v217, v213, v220
	v_cmp_ge_f32_e64 s[60:61], 0, v218
	s_nop 1
	v_cndmask_b32_e64 v213, v213, v216, s[60:61]
	v_cmp_lt_f32_e64 s[60:61], 0, v219
	s_nop 1
	v_cndmask_b32_e64 v213, v213, v217, s[60:61]
	v_mul_f32_e32 v216, 0x37800000, v213
	v_cndmask_b32_e32 v213, v213, v216, vcc
	v_cmp_class_f32_e32 vcc, v220, v201
	s_nop 1
	v_cndmask_b32_e32 v220, v213, v220, vcc
	v_div_scale_f32 v216, s[60:61], v220, v220, 1.0
	v_rcp_f32_e32 v213, v216
	v_div_scale_f32 v217, vcc, 1.0, v220, 1.0
	v_fma_f32 v218, -v216, v213, 1.0
	v_fmac_f32_e32 v213, v218, v213
	v_mul_f32_e32 v218, v217, v213
	v_fma_f32 v219, -v216, v218, v217
	v_fmac_f32_e32 v218, v219, v213
	v_fma_f32 v216, -v216, v218, v217
	v_div_fmas_f32 v216, v216, v213, v218
	v_div_fixup_f32 v220, v216, v220, 1.0
	v_lshlrev_b32_e32 v204, 16, v176
	v_and_b32_e32 v205, 0xffff0000, v176
	v_lshlrev_b32_e32 v206, 16, v177
	v_and_b32_e32 v207, 0xffff0000, v177
	v_lshlrev_b32_e32 v208, 16, v178
	v_and_b32_e32 v209, 0xffff0000, v178
	v_lshlrev_b32_e32 v210, 16, v179
	v_and_b32_e32 v211, 0xffff0000, v179
	v_mov_b32_e32 v202, v220
	v_pk_mul_f32 v[204:205], v[202:203], v[204:205] op_sel_hi:[0,1]
	v_pk_mul_f32 v[206:207], v[202:203], v[206:207] op_sel_hi:[0,1]
	v_pk_mul_f32 v[208:209], v[202:203], v[208:209] op_sel_hi:[0,1]
	v_pk_mul_f32 v[210:211], v[202:203], v[210:211] op_sel_hi:[0,1]
	v_pk_mul_f32 v[204:205], v[36:37], v[204:205]
	v_pk_mul_f32 v[206:207], v[38:39], v[206:207]
	v_pk_mul_f32 v[208:209], v[40:41], v[208:209]
	v_pk_mul_f32 v[210:211], v[42:43], v[210:211]
	global_store_dwordx4 v33, v[204:207], s[42:43]
	global_store_dwordx4 v33, v[208:211], s[42:43] offset:16
	s_add_u32 s42, s42, 0x400000
	s_addc_u32 s43, s43, 0
	global_load_dwordx4 v[176:179], v32, s[38:39]
	global_load_dwordx2 v[192:193], v34, s[46:47]
	s_add_u32 s38, s38, 0x200000
	s_addc_u32 s39, s39, 0
	s_add_u32 s46, s46, 0x2000
	s_addc_u32 s47, s47, 0
	s_waitcnt vmcnt(12)
	v_ffbh_u32_e32 v212, v195
	v_min_u32_e32 v212, 32, v212
	v_lshlrev_b64 v[214:215], v212, v[194:195]
	v_min_u32_e32 v214, 1, v214
	v_or_b32_e32 v214, v215, v214
	v_cvt_f32_u32_e32 v214, v214
	v_sub_u32_e32 v212, 32, v212
	v_ldexp_f32 v220, v214, v212
	v_fmamk_f32 v220, v220, 0x30800000, v200
	v_mul_f32_e32 v213, 0x4f800000, v220
	v_cmp_gt_f32_e32 vcc, s63, v220
	s_nop 1
	v_cndmask_b32_e32 v220, v220, v213, vcc
	v_sqrt_f32_e32 v213, v220
	s_nop 0
	v_add_u32_e32 v216, -1, v213
	v_add_u32_e32 v217, 1, v213
	v_fma_f32 v218, -v216, v213, v220
	v_fma_f32 v219, -v217, v213, v220
	v_cmp_ge_f32_e64 s[60:61], 0, v218
	s_nop 1
	v_cndmask_b32_e64 v213, v213, v216, s[60:61]
	v_cmp_lt_f32_e64 s[60:61], 0, v219
	s_nop 1
	v_cndmask_b32_e64 v213, v213, v217, s[60:61]
	v_mul_f32_e32 v216, 0x37800000, v213
	v_cndmask_b32_e32 v213, v213, v216, vcc
	v_cmp_class_f32_e32 vcc, v220, v201
	s_nop 1
	v_cndmask_b32_e32 v220, v213, v220, vcc
	v_div_scale_f32 v216, s[60:61], v220, v220, 1.0
	v_rcp_f32_e32 v213, v216
	v_div_scale_f32 v217, vcc, 1.0, v220, 1.0
	v_fma_f32 v218, -v216, v213, 1.0
	v_fmac_f32_e32 v213, v218, v213
	v_mul_f32_e32 v218, v217, v213
	v_fma_f32 v219, -v216, v218, v217
	v_fmac_f32_e32 v218, v219, v213
	v_fma_f32 v216, -v216, v218, v217
	v_div_fmas_f32 v216, v216, v213, v218
	v_div_fixup_f32 v220, v216, v220, 1.0
	v_lshlrev_b32_e32 v204, 16, v180
	v_and_b32_e32 v205, 0xffff0000, v180
	v_lshlrev_b32_e32 v206, 16, v181
	v_and_b32_e32 v207, 0xffff0000, v181
	v_lshlrev_b32_e32 v208, 16, v182
	v_and_b32_e32 v209, 0xffff0000, v182
	v_lshlrev_b32_e32 v210, 16, v183
	v_and_b32_e32 v211, 0xffff0000, v183
	v_mov_b32_e32 v202, v220
	v_pk_mul_f32 v[204:205], v[202:203], v[204:205] op_sel_hi:[0,1]
	v_pk_mul_f32 v[206:207], v[202:203], v[206:207] op_sel_hi:[0,1]
	v_pk_mul_f32 v[208:209], v[202:203], v[208:209] op_sel_hi:[0,1]
	v_pk_mul_f32 v[210:211], v[202:203], v[210:211] op_sel_hi:[0,1]
	v_pk_mul_f32 v[204:205], v[36:37], v[204:205]
	v_pk_mul_f32 v[206:207], v[38:39], v[206:207]
	v_pk_mul_f32 v[208:209], v[40:41], v[208:209]
	v_pk_mul_f32 v[210:211], v[42:43], v[210:211]
	global_store_dwordx4 v33, v[204:207], s[42:43]
	global_store_dwordx4 v33, v[208:211], s[42:43] offset:16
	s_add_u32 s42, s42, 0x400000
	s_addc_u32 s43, s43, 0
	global_load_dwordx4 v[180:183], v32, s[38:39]
	global_load_dwordx2 v[194:195], v34, s[46:47]
	s_add_u32 s38, s38, 0x200000
	s_addc_u32 s39, s39, 0
	s_add_u32 s46, s46, 0x2000
	s_addc_u32 s47, s47, 0
	s_waitcnt vmcnt(12)
; __global__ void __launch_bounds__(NTHR, 2) mega(Params p) {
;     ...
;         for (size_t idx = (size_t)bid * NTHR + tid; idx < (size_t)16384 * DM / 8; idx += (size_t)G * NTHR) { const int r = 16384 + (int)(idx >> 7), c = (int)(idx & 127) * 8;
;             const u32x4 q = *(const u32x4*)(xh + (size_t)r * DM + c); const u32x4 q2 = *(const u32x4*)(xh + (size_t)(r - 16384) * DM + c);
;             *(u32x4*)(xcp + (size_t)(r - 16384) * DM + c) = q2;
;             const float rs = 1.0f / sqrtf((float)ssF[r] * SSKI + EPSN); const f32x4 g0 = *(const f32x4*)(p.g_final + c), g1 = *(const f32x4*)(p.g_final + c + 4);
;             f32x4 v0 = {__uint_as_float(q.x << 16), __uint_as_float(q.x & 0xffff0000u), __uint_as_float(q.y << 16), __uint_as_float(q.y & 0xffff0000u)};
;             f32x4 v1 = {__uint_as_float(q.z << 16), __uint_as_float(q.z & 0xffff0000u), __uint_as_float(q.w << 16), __uint_as_float(q.w & 0xffff0000u)};
;             *(f32x4*)(p.out + (size_t)r * DM + c) = v0 * rs * g0; *(f32x4*)(p.out + (size_t)r * DM + c + 4) = v1 * rs * g1; }
	v_ffbh_u32_e32 v212, v197
	v_min_u32_e32 v212, 32, v212
	v_lshlrev_b64 v[214:215], v212, v[196:197]
	v_min_u32_e32 v214, 1, v214
	v_or_b32_e32 v214, v215, v214
	v_cvt_f32_u32_e32 v214, v214
	v_sub_u32_e32 v212, 32, v212
	v_ldexp_f32 v220, v214, v212
	v_fmamk_f32 v220, v220, 0x30800000, v200
	v_mul_f32_e32 v213, 0x4f800000, v220
	v_cmp_gt_f32_e32 vcc, s63, v220
	s_nop 1
	v_cndmask_b32_e32 v220, v220, v213, vcc
	v_sqrt_f32_e32 v213, v220
	s_nop 0
	v_add_u32_e32 v216, -1, v213
	v_add_u32_e32 v217, 1, v213
	v_fma_f32 v218, -v216, v213, v220
	v_fma_f32 v219, -v217, v213, v220
	v_cmp_ge_f32_e64 s[60:61], 0, v218
	s_nop 1
	v_cndmask_b32_e64 v213, v213, v216, s[60:61]
	v_cmp_lt_f32_e64 s[60:61], 0, v219
	s_nop 1
	v_cndmask_b32_e64 v213, v213, v217, s[60:61]
	v_mul_f32_e32 v216, 0x37800000, v213
	v_cndmask_b32_e32 v213, v213, v216, vcc
	v_cmp_class_f32_e32 vcc, v220, v201
	s_nop 1
	v_cndmask_b32_e32 v220, v213, v220, vcc
	v_div_scale_f32 v216, s[60:61], v220, v220, 1.0
	v_rcp_f32_e32 v213, v216
	v_div_scale_f32 v217, vcc, 1.0, v220, 1.0
	v_fma_f32 v218, -v216, v213, 1.0
	v_fmac_f32_e32 v213, v218, v213
	v_mul_f32_e32 v218, v217, v213
	v_fma_f32 v219, -v216, v218, v217
	v_fmac_f32_e32 v218, v219, v213
	v_fma_f32 v216, -v216, v218, v217
	v_div_fmas_f32 v216, v216, v213, v218
	v_div_fixup_f32 v220, v216, v220, 1.0
	v_lshlrev_b32_e32 v204, 16, v184
	v_and_b32_e32 v205, 0xffff0000, v184
	v_lshlrev_b32_e32 v206, 16, v185
	v_and_b32_e32 v207, 0xffff0000, v185
	v_lshlrev_b32_e32 v208, 16, v186
	v_and_b32_e32 v209, 0xffff0000, v186
	v_lshlrev_b32_e32 v210, 16, v187
	v_and_b32_e32 v211, 0xffff0000, v187
	v_mov_b32_e32 v202, v220
	v_pk_mul_f32 v[204:205], v[202:203], v[204:205] op_sel_hi:[0,1]
	v_pk_mul_f32 v[206:207], v[202:203], v[206:207] op_sel_hi:[0,1]
	v_pk_mul_f32 v[208:209], v[202:203], v[208:209] op_sel_hi:[0,1]
	v_pk_mul_f32 v[210:211], v[202:203], v[210:211] op_sel_hi:[0,1]
	v_pk_mul_f32 v[204:205], v[36:37], v[204:205]
	v_pk_mul_f32 v[206:207], v[38:39], v[206:207]
	v_pk_mul_f32 v[208:209], v[40:41], v[208:209]
	v_pk_mul_f32 v[210:211], v[42:43], v[210:211]
	global_store_dwordx4 v33, v[204:207], s[42:43]
	global_store_dwordx4 v33, v[208:211], s[42:43] offset:16
	s_add_u32 s42, s42, 0x400000
	s_addc_u32 s43, s43, 0
	global_load_dwordx4 v[184:187], v32, s[38:39]
	global_load_dwordx2 v[196:197], v34, s[46:47]
	s_add_u32 s38, s38, 0x200000
	s_addc_u32 s39, s39, 0
	s_add_u32 s46, s46, 0x2000
	s_addc_u32 s47, s47, 0
	s_waitcnt vmcnt(12)
	v_ffbh_u32_e32 v212, v199
	v_min_u32_e32 v212, 32, v212
	v_lshlrev_b64 v[214:215], v212, v[198:199]
	v_min_u32_e32 v214, 1, v214
	v_or_b32_e32 v214, v215, v214
	v_cvt_f32_u32_e32 v214, v214
	v_sub_u32_e32 v212, 32, v212
	v_ldexp_f32 v220, v214, v212
	v_fmamk_f32 v220, v220, 0x30800000, v200
	v_mul_f32_e32 v213, 0x4f800000, v220
	v_cmp_gt_f32_e32 vcc, s63, v220
	s_nop 1
	v_cndmask_b32_e32 v220, v220, v213, vcc
	v_sqrt_f32_e32 v213, v220
	s_nop 0
	v_add_u32_e32 v216, -1, v213
	v_add_u32_e32 v217, 1, v213
	v_fma_f32 v218, -v216, v213, v220
	v_fma_f32 v219, -v217, v213, v220
	v_cmp_ge_f32_e64 s[60:61], 0, v218
	s_nop 1
	v_cndmask_b32_e64 v213, v213, v216, s[60:61]
	v_cmp_lt_f32_e64 s[60:61], 0, v219
	s_nop 1
	v_cndmask_b32_e64 v213, v213, v217, s[60:61]
	v_mul_f32_e32 v216, 0x37800000, v213
	v_cndmask_b32_e32 v213, v213, v216, vcc
	v_cmp_class_f32_e32 vcc, v220, v201
	s_nop 1
	v_cndmask_b32_e32 v220, v213, v220, vcc
	v_div_scale_f32 v216, s[60:61], v220, v220, 1.0
	v_rcp_f32_e32 v213, v216
	v_div_scale_f32 v217, vcc, 1.0, v220, 1.0
	v_fma_f32 v218, -v216, v213, 1.0
	v_fmac_f32_e32 v213, v218, v213
	v_mul_f32_e32 v218, v217, v213
	v_fma_f32 v219, -v216, v218, v217
	v_fmac_f32_e32 v218, v219, v213
	v_fma_f32 v216, -v216, v218, v217
	v_div_fmas_f32 v216, v216, v213, v218
	v_div_fixup_f32 v220, v216, v220, 1.0
	v_lshlrev_b32_e32 v204, 16, v188
	v_and_b32_e32 v205, 0xffff0000, v188
	v_lshlrev_b32_e32 v206, 16, v189
	v_and_b32_e32 v207, 0xffff0000, v189
	v_lshlrev_b32_e32 v208, 16, v190
	v_and_b32_e32 v209, 0xffff0000, v190
	v_lshlrev_b32_e32 v210, 16, v191
	v_and_b32_e32 v211, 0xffff0000, v191
	v_mov_b32_e32 v202, v220
	v_pk_mul_f32 v[204:205], v[202:203], v[204:205] op_sel_hi:[0,1]
	v_pk_mul_f32 v[206:207], v[202:203], v[206:207] op_sel_hi:[0,1]
	v_pk_mul_f32 v[208:209], v[202:203], v[208:209] op_sel_hi:[0,1]
	v_pk_mul_f32 v[210:211], v[202:203], v[210:211] op_sel_hi:[0,1]
	v_pk_mul_f32 v[204:205], v[36:37], v[204:205]
	v_pk_mul_f32 v[206:207], v[38:39], v[206:207]
	v_pk_mul_f32 v[208:209], v[40:41], v[208:209]
	v_pk_mul_f32 v[210:211], v[42:43], v[210:211]
	global_store_dwordx4 v33, v[204:207], s[42:43]
	global_store_dwordx4 v33, v[208:211], s[42:43] offset:16
	s_add_u32 s42, s42, 0x400000
	s_addc_u32 s43, s43, 0
	global_load_dwordx4 v[188:191], v32, s[38:39]
	global_load_dwordx2 v[198:199], v34, s[46:47]
	s_add_u32 s38, s38, 0x200000
	s_addc_u32 s39, s39, 0
	s_add_u32 s46, s46, 0x2000
	s_addc_u32 s47, s47, 0
	s_waitcnt vmcnt(12)
; __global__ void __launch_bounds__(NTHR, 2) mega(Params p) {
;     ...
;         for (size_t idx = (size_t)bid * NTHR + tid; idx < (size_t)16384 * DM / 8; idx += (size_t)G * NTHR) { const int r = 16384 + (int)(idx >> 7), c = (int)(idx & 127) * 8;
;             const u32x4 q = *(const u32x4*)(xh + (size_t)r * DM + c); const u32x4 q2 = *(const u32x4*)(xh + (size_t)(r - 16384) * DM + c);
;             *(u32x4*)(xcp + (size_t)(r - 16384) * DM + c) = q2;
;             const float rs = 1.0f / sqrtf((float)ssF[r] * SSKI + EPSN); const f32x4 g0 = *(const f32x4*)(p.g_final + c), g1 = *(const f32x4*)(p.g_final + c + 4);
;             f32x4 v0 = {__uint_as_float(q.x << 16), __uint_as_float(q.x & 0xffff0000u), __uint_as_float(q.y << 16), __uint_as_float(q.y & 0xffff0000u)};
;             f32x4 v1 = {__uint_as_float(q.z << 16), __uint_as_float(q.z & 0xffff0000u), __uint_as_float(q.w << 16), __uint_as_float(q.w & 0xffff0000u)};
;             *(f32x4*)(p.out + (size_t)r * DM + c) = v0 * rs * g0; *(f32x4*)(p.out + (size_t)r * DM + c + 4) = v1 * rs * g1; }
	v_ffbh_u32_e32 v212, v193
	v_min_u32_e32 v212, 32, v212
	v_lshlrev_b64 v[214:215], v212, v[192:193]
	v_min_u32_e32 v214, 1, v214
	v_or_b32_e32 v214, v215, v214
	v_cvt_f32_u32_e32 v214, v214
	v_sub_u32_e32 v212, 32, v212
	v_ldexp_f32 v220, v214, v212
	v_fmamk_f32 v220, v220, 0x30800000, v200
	v_mul_f32_e32 v213, 0x4f800000, v220
	v_cmp_gt_f32_e32 vcc, s63, v220
	s_nop 1
	v_cndmask_b32_e32 v220, v220, v213, vcc
	v_sqrt_f32_e32 v213, v220
	s_nop 0
	v_add_u32_e32 v216, -1, v213
	v_add_u32_e32 v217, 1, v213
	v_fma_f32 v218, -v216, v213, v220
	v_fma_f32 v219, -v217, v213, v220
	v_cmp_ge_f32_e64 s[60:61], 0, v218
	s_nop 1
	v_cndmask_b32_e64 v213, v213, v216, s[60:61]
	v_cmp_lt_f32_e64 s[60:61], 0, v219
	s_nop 1
	v_cndmask_b32_e64 v213, v213, v217, s[60:61]
	v_mul_f32_e32 v216, 0x37800000, v213
	v_cndmask_b32_e32 v213, v213, v216, vcc
	v_cmp_class_f32_e32 vcc, v220, v201
	s_nop 1
	v_cndmask_b32_e32 v220, v213, v220, vcc
	v_div_scale_f32 v216, s[60:61], v220, v220, 1.0
	v_rcp_f32_e32 v213, v216
	v_div_scale_f32 v217, vcc, 1.0, v220, 1.0
	v_fma_f32 v218, -v216, v213, 1.0
	v_fmac_f32_e32 v213, v218, v213
	v_mul_f32_e32 v218, v217, v213
	v_fma_f32 v219, -v216, v218, v217
	v_fmac_f32_e32 v218, v219, v213
	v_fma_f32 v216, -v216, v218, v217
	v_div_fmas_f32 v216, v216, v213, v218
	v_div_fixup_f32 v220, v216, v220, 1.0
	v_lshlrev_b32_e32 v204, 16, v176
	v_and_b32_e32 v205, 0xffff0000, v176
	v_lshlrev_b32_e32 v206, 16, v177
	v_and_b32_e32 v207, 0xffff0000, v177
	v_lshlrev_b32_e32 v208, 16, v178
	v_and_b32_e32 v209, 0xffff0000, v178
	v_lshlrev_b32_e32 v210, 16, v179
	v_and_b32_e32 v211, 0xffff0000, v179
	v_mov_b32_e32 v202, v220
	v_pk_mul_f32 v[204:205], v[202:203], v[204:205] op_sel_hi:[0,1]
	v_pk_mul_f32 v[206:207], v[202:203], v[206:207] op_sel_hi:[0,1]
	v_pk_mul_f32 v[208:209], v[202:203], v[208:209] op_sel_hi:[0,1]
	v_pk_mul_f32 v[210:211], v[202:203], v[210:211] op_sel_hi:[0,1]
	v_pk_mul_f32 v[204:205], v[36:37], v[204:205]
	v_pk_mul_f32 v[206:207], v[38:39], v[206:207]
	v_pk_mul_f32 v[208:209], v[40:41], v[208:209]
	v_pk_mul_f32 v[210:211], v[42:43], v[210:211]
	global_store_dwordx4 v33, v[204:207], s[42:43]
	global_store_dwordx4 v33, v[208:211], s[42:43] offset:16
	s_add_u32 s42, s42, 0x400000
	s_addc_u32 s43, s43, 0
	s_waitcnt vmcnt(10)
	v_ffbh_u32_e32 v212, v195
	v_min_u32_e32 v212, 32, v212
	v_lshlrev_b64 v[214:215], v212, v[194:195]
	v_min_u32_e32 v214, 1, v214
	v_or_b32_e32 v214, v215, v214
	v_cvt_f32_u32_e32 v214, v214
	v_sub_u32_e32 v212, 32, v212
	v_ldexp_f32 v220, v214, v212
	v_fmamk_f32 v220, v220, 0x30800000, v200
	v_mul_f32_e32 v213, 0x4f800000, v220
	v_cmp_gt_f32_e32 vcc, s63, v220
	s_nop 1
	v_cndmask_b32_e32 v220, v220, v213, vcc
	v_sqrt_f32_e32 v213, v220
	s_nop 0
	v_add_u32_e32 v216, -1, v213
	v_add_u32_e32 v217, 1, v213
	v_fma_f32 v218, -v216, v213, v220
	v_fma_f32 v219, -v217, v213, v220
	v_cmp_ge_f32_e64 s[60:61], 0, v218
	s_nop 1
	v_cndmask_b32_e64 v213, v213, v216, s[60:61]
	v_cmp_lt_f32_e64 s[60:61], 0, v219
	s_nop 1
	v_cndmask_b32_e64 v213, v213, v217, s[60:61]
	v_mul_f32_e32 v216, 0x37800000, v213
	v_cndmask_b32_e32 v213, v213, v216, vcc
	v_cmp_class_f32_e32 vcc, v220, v201
	s_nop 1
	v_cndmask_b32_e32 v220, v213, v220, vcc
	v_div_scale_f32 v216, s[60:61], v220, v220, 1.0
	v_rcp_f32_e32 v213, v216
	v_div_scale_f32 v217, vcc, 1.0, v220, 1.0
	v_fma_f32 v218, -v216, v213, 1.0
	v_fmac_f32_e32 v213, v218, v213
	v_mul_f32_e32 v218, v217, v213
	v_fma_f32 v219, -v216, v218, v217
	v_fmac_f32_e32 v218, v219, v213
	v_fma_f32 v216, -v216, v218, v217
	v_div_fmas_f32 v216, v216, v213, v218
	v_div_fixup_f32 v220, v216, v220, 1.0
	v_lshlrev_b32_e32 v204, 16, v180
	v_and_b32_e32 v205, 0xffff0000, v180
	v_lshlrev_b32_e32 v206, 16, v181
	v_and_b32_e32 v207, 0xffff0000, v181
	v_lshlrev_b32_e32 v208, 16, v182
	v_and_b32_e32 v209, 0xffff0000, v182
	v_lshlrev_b32_e32 v210, 16, v183
	v_and_b32_e32 v211, 0xffff0000, v183
	v_mov_b32_e32 v202, v220
	v_pk_mul_f32 v[204:205], v[202:203], v[204:205] op_sel_hi:[0,1]
	v_pk_mul_f32 v[206:207], v[202:203], v[206:207] op_sel_hi:[0,1]
	v_pk_mul_f32 v[208:209], v[202:203], v[208:209] op_sel_hi:[0,1]
	v_pk_mul_f32 v[210:211], v[202:203], v[210:211] op_sel_hi:[0,1]
	v_pk_mul_f32 v[204:205], v[36:37], v[204:205]
	v_pk_mul_f32 v[206:207], v[38:39], v[206:207]
	v_pk_mul_f32 v[208:209], v[40:41], v[208:209]
	v_pk_mul_f32 v[210:211], v[42:43], v[210:211]
	global_store_dwordx4 v33, v[204:207], s[42:43]
	global_store_dwordx4 v33, v[208:211], s[42:43] offset:16
	s_add_u32 s42, s42, 0x400000
	s_addc_u32 s43, s43, 0
	s_waitcnt vmcnt(8)
; __global__ void __launch_bounds__(NTHR, 2) mega(Params p) {
;     ...
;         for (size_t idx = (size_t)bid * NTHR + tid; idx < (size_t)16384 * DM / 8; idx += (size_t)G * NTHR) { const int r = 16384 + (int)(idx >> 7), c = (int)(idx & 127) * 8;
;             const u32x4 q = *(const u32x4*)(xh + (size_t)r * DM + c); const u32x4 q2 = *(const u32x4*)(xh + (size_t)(r - 16384) * DM + c);
;             *(u32x4*)(xcp + (size_t)(r - 16384) * DM + c) = q2;
;             const float rs = 1.0f / sqrtf((float)ssF[r] * SSKI + EPSN); const f32x4 g0 = *(const f32x4*)(p.g_final + c), g1 = *(const f32x4*)(p.g_final + c + 4);
;             f32x4 v0 = {__uint_as_float(q.x << 16), __uint_as_float(q.x & 0xffff0000u), __uint_as_float(q.y << 16), __uint_as_float(q.y & 0xffff0000u)};
;             f32x4 v1 = {__uint_as_float(q.z << 16), __uint_as_float(q.z & 0xffff0000u), __uint_as_float(q.w << 16), __uint_as_float(q.w & 0xffff0000u)};
;             *(f32x4*)(p.out + (size_t)r * DM + c) = v0 * rs * g0; *(f32x4*)(p.out + (size_t)r * DM + c + 4) = v1 * rs * g1; }
;     ...
;             const float rs = 1.0f / sqrtf((float)ssF[r] * SSKI + EPSN); const f32x4 g0 = *(const f32x4*)(p.g_final + c), g1 = *(const f32x4*)(p.g_final + c + 4);
	v_ffbh_u32_e32 v212, v197
	v_min_u32_e32 v212, 32, v212
	v_lshlrev_b64 v[214:215], v212, v[196:197]
	v_min_u32_e32 v214, 1, v214
	v_or_b32_e32 v214, v215, v214
	v_cvt_f32_u32_e32 v214, v214
	v_sub_u32_e32 v212, 32, v212
	v_ldexp_f32 v220, v214, v212
	v_fmamk_f32 v220, v220, 0x30800000, v200
	v_mul_f32_e32 v213, 0x4f800000, v220
	v_cmp_gt_f32_e32 vcc, s63, v220
	s_nop 1
	v_cndmask_b32_e32 v220, v220, v213, vcc
	v_sqrt_f32_e32 v213, v220
	s_nop 0
	v_add_u32_e32 v216, -1, v213
	v_add_u32_e32 v217, 1, v213
	v_fma_f32 v218, -v216, v213, v220
	v_fma_f32 v219, -v217, v213, v220
	v_cmp_ge_f32_e64 s[60:61], 0, v218
	s_nop 1
	v_cndmask_b32_e64 v213, v213, v216, s[60:61]
	v_cmp_lt_f32_e64 s[60:61], 0, v219
	s_nop 1
	v_cndmask_b32_e64 v213, v213, v217, s[60:61]
	v_mul_f32_e32 v216, 0x37800000, v213
	v_cndmask_b32_e32 v213, v213, v216, vcc
	v_cmp_class_f32_e32 vcc, v220, v201
	s_nop 1
	v_cndmask_b32_e32 v220, v213, v220, vcc
	v_div_scale_f32 v216, s[60:61], v220, v220, 1.0
	v_rcp_f32_e32 v213, v216
	v_div_scale_f32 v217, vcc, 1.0, v220, 1.0
	v_fma_f32 v218, -v216, v213, 1.0
	v_fmac_f32_e32 v213, v218, v213
	v_mul_f32_e32 v218, v217, v213
	v_fma_f32 v219, -v216, v218, v217
	v_fmac_f32_e32 v218, v219, v213
	v_fma_f32 v216, -v216, v218, v217
	v_div_fmas_f32 v216, v216, v213, v218
	v_div_fixup_f32 v220, v216, v220, 1.0
	v_lshlrev_b32_e32 v204, 16, v184
	v_and_b32_e32 v205, 0xffff0000, v184
	v_lshlrev_b32_e32 v206, 16, v185
	v_and_b32_e32 v207, 0xffff0000, v185
	v_lshlrev_b32_e32 v208, 16, v186
	v_and_b32_e32 v209, 0xffff0000, v186
	v_lshlrev_b32_e32 v210, 16, v187
	v_and_b32_e32 v211, 0xffff0000, v187
	v_mov_b32_e32 v202, v220
	v_pk_mul_f32 v[204:205], v[202:203], v[204:205] op_sel_hi:[0,1]
	v_pk_mul_f32 v[206:207], v[202:203], v[206:207] op_sel_hi:[0,1]
	v_pk_mul_f32 v[208:209], v[202:203], v[208:209] op_sel_hi:[0,1]
	v_pk_mul_f32 v[210:211], v[202:203], v[210:211] op_sel_hi:[0,1]
	v_pk_mul_f32 v[204:205], v[36:37], v[204:205]
	v_pk_mul_f32 v[206:207], v[38:39], v[206:207]
	v_pk_mul_f32 v[208:209], v[40:41], v[208:209]
	v_pk_mul_f32 v[210:211], v[42:43], v[210:211]
	global_store_dwordx4 v33, v[204:207], s[42:43]
	global_store_dwordx4 v33, v[208:211], s[42:43] offset:16
	s_add_u32 s42, s42, 0x400000
	s_addc_u32 s43, s43, 0
	s_waitcnt vmcnt(6)
	v_ffbh_u32_e32 v212, v199
	v_min_u32_e32 v212, 32, v212
	v_lshlrev_b64 v[214:215], v212, v[198:199]
	v_min_u32_e32 v214, 1, v214
	v_or_b32_e32 v214, v215, v214
	v_cvt_f32_u32_e32 v214, v214
	v_sub_u32_e32 v212, 32, v212
	v_ldexp_f32 v220, v214, v212
	v_fmamk_f32 v220, v220, 0x30800000, v200
	v_mul_f32_e32 v213, 0x4f800000, v220
	v_cmp_gt_f32_e32 vcc, s63, v220
	s_nop 1
	v_cndmask_b32_e32 v220, v220, v213, vcc
	v_sqrt_f32_e32 v213, v220
	s_nop 0
	v_add_u32_e32 v216, -1, v213
	v_add_u32_e32 v217, 1, v213
	v_fma_f32 v218, -v216, v213, v220
	v_fma_f32 v219, -v217, v213, v220
	v_cmp_ge_f32_e64 s[60:61], 0, v218
	s_nop 1
	v_cndmask_b32_e64 v213, v213, v216, s[60:61]
	v_cmp_lt_f32_e64 s[60:61], 0, v219
	s_nop 1
	v_cndmask_b32_e64 v213, v213, v217, s[60:61]
	v_mul_f32_e32 v216, 0x37800000, v213
	v_cndmask_b32_e32 v213, v213, v216, vcc
	v_cmp_class_f32_e32 vcc, v220, v201
	s_nop 1
	v_cndmask_b32_e32 v220, v213, v220, vcc
	v_div_scale_f32 v216, s[60:61], v220, v220, 1.0
	v_rcp_f32_e32 v213, v216
	v_div_scale_f32 v217, vcc, 1.0, v220, 1.0
	v_fma_f32 v218, -v216, v213, 1.0
	v_fmac_f32_e32 v213, v218, v213
	v_mul_f32_e32 v218, v217, v213
	v_fma_f32 v219, -v216, v218, v217
	v_fmac_f32_e32 v218, v219, v213
	v_fma_f32 v216, -v216, v218, v217
	v_div_fmas_f32 v216, v216, v213, v218
	v_div_fixup_f32 v220, v216, v220, 1.0
	v_lshlrev_b32_e32 v204, 16, v188
	v_and_b32_e32 v205, 0xffff0000, v188
	v_lshlrev_b32_e32 v206, 16, v189
	v_and_b32_e32 v207, 0xffff0000, v189
	v_lshlrev_b32_e32 v208, 16, v190
	v_and_b32_e32 v209, 0xffff0000, v190
	v_lshlrev_b32_e32 v210, 16, v191
	v_and_b32_e32 v211, 0xffff0000, v191
	v_mov_b32_e32 v202, v220
	v_pk_mul_f32 v[204:205], v[202:203], v[204:205] op_sel_hi:[0,1]
	v_pk_mul_f32 v[206:207], v[202:203], v[206:207] op_sel_hi:[0,1]
	v_pk_mul_f32 v[208:209], v[202:203], v[208:209] op_sel_hi:[0,1]
	v_pk_mul_f32 v[210:211], v[202:203], v[210:211] op_sel_hi:[0,1]
	v_pk_mul_f32 v[204:205], v[36:37], v[204:205]
	v_pk_mul_f32 v[206:207], v[38:39], v[206:207]
	v_pk_mul_f32 v[208:209], v[40:41], v[208:209]
	v_pk_mul_f32 v[210:211], v[42:43], v[210:211]
	global_store_dwordx4 v33, v[204:207], s[42:43]
	global_store_dwordx4 v33, v[208:211], s[42:43] offset:16
	s_add_u32 s42, s42, 0x400000
	s_addc_u32 s43, s43, 0
	v_ffbh_u32_e32 v212, v129
	v_min_u32_e32 v212, 32, v212
	v_lshlrev_b64 v[214:215], v212, v[128:129]
	v_min_u32_e32 v214, 1, v214
	v_or_b32_e32 v214, v215, v214
	v_cvt_f32_u32_e32 v214, v214
	v_sub_u32_e32 v212, 32, v212
	v_ldexp_f32 v160, v214, v212
	v_fmamk_f32 v160, v160, 0x30800000, v200
	v_mul_f32_e32 v213, 0x4f800000, v160
	v_cmp_gt_f32_e32 vcc, s63, v160
	s_nop 1
	v_cndmask_b32_e32 v160, v160, v213, vcc
	v_sqrt_f32_e32 v213, v160
	s_nop 0
	v_add_u32_e32 v216, -1, v213
	v_add_u32_e32 v217, 1, v213
	v_fma_f32 v218, -v216, v213, v160
	v_fma_f32 v219, -v217, v213, v160
	v_cmp_ge_f32_e64 s[60:61], 0, v218
	s_nop 1
	v_cndmask_b32_e64 v213, v213, v216, s[60:61]
	v_cmp_lt_f32_e64 s[60:61], 0, v219
	s_nop 1
	v_cndmask_b32_e64 v213, v213, v217, s[60:61]
	v_mul_f32_e32 v216, 0x37800000, v213
	v_cndmask_b32_e32 v213, v213, v216, vcc
	v_cmp_class_f32_e32 vcc, v160, v201
	s_nop 1
	v_cndmask_b32_e32 v160, v213, v160, vcc
	v_div_scale_f32 v216, s[60:61], v160, v160, 1.0
	v_rcp_f32_e32 v213, v216
	v_div_scale_f32 v217, vcc, 1.0, v160, 1.0
	v_fma_f32 v218, -v216, v213, 1.0
	v_fmac_f32_e32 v213, v218, v213
; __global__ void __launch_bounds__(NTHR, 2) mega(Params p) {
;     ...
;             const float rs = 1.0f / sqrtf((float)ssF[r] * SSKI + EPSN); const f32x4 g0 = *(const f32x4*)(p.g_final + c), g1 = *(const f32x4*)(p.g_final + c + 4);
	v_mul_f32_e32 v218, v217, v213
	v_fma_f32 v219, -v216, v218, v217
	v_fmac_f32_e32 v218, v219, v213
	v_fma_f32 v216, -v216, v218, v217
	v_div_fmas_f32 v216, v216, v213, v218
	v_div_fixup_f32 v160, v216, v160, 1.0
	v_ffbh_u32_e32 v212, v131
	v_min_u32_e32 v212, 32, v212
	v_lshlrev_b64 v[214:215], v212, v[130:131]
	v_min_u32_e32 v214, 1, v214
	v_or_b32_e32 v214, v215, v214
	v_cvt_f32_u32_e32 v214, v214
	v_sub_u32_e32 v212, 32, v212
	v_ldexp_f32 v161, v214, v212
	v_fmamk_f32 v161, v161, 0x30800000, v200
	v_mul_f32_e32 v213, 0x4f800000, v161
	v_cmp_gt_f32_e32 vcc, s63, v161
	s_nop 1
	v_cndmask_b32_e32 v161, v161, v213, vcc
	v_sqrt_f32_e32 v213, v161
	s_nop 0
	v_add_u32_e32 v216, -1, v213
	v_add_u32_e32 v217, 1, v213
	v_fma_f32 v218, -v216, v213, v161
	v_fma_f32 v219, -v217, v213, v161
	v_cmp_ge_f32_e64 s[60:61], 0, v218
	s_nop 1
	v_cndmask_b32_e64 v213, v213, v216, s[60:61]
	v_cmp_lt_f32_e64 s[60:61], 0, v219
	s_nop 1
	v_cndmask_b32_e64 v213, v213, v217, s[60:61]
	v_mul_f32_e32 v216, 0x37800000, v213
	v_cndmask_b32_e32 v213, v213, v216, vcc
	v_cmp_class_f32_e32 vcc, v161, v201
	s_nop 1
	v_cndmask_b32_e32 v161, v213, v161, vcc
	v_div_scale_f32 v216, s[60:61], v161, v161, 1.0
	v_rcp_f32_e32 v213, v216
	v_div_scale_f32 v217, vcc, 1.0, v161, 1.0
	v_fma_f32 v218, -v216, v213, 1.0
	v_fmac_f32_e32 v213, v218, v213
	v_mul_f32_e32 v218, v217, v213
	v_fma_f32 v219, -v216, v218, v217
	v_fmac_f32_e32 v218, v219, v213
	v_fma_f32 v216, -v216, v218, v217
	v_div_fmas_f32 v216, v216, v213, v218
	v_div_fixup_f32 v161, v216, v161, 1.0
	v_ffbh_u32_e32 v212, v133
	v_min_u32_e32 v212, 32, v212
	v_lshlrev_b64 v[214:215], v212, v[132:133]
	v_min_u32_e32 v214, 1, v214
	v_or_b32_e32 v214, v215, v214
	v_cvt_f32_u32_e32 v214, v214
	v_sub_u32_e32 v212, 32, v212
	v_ldexp_f32 v162, v214, v212
	v_fmamk_f32 v162, v162, 0x30800000, v200
	v_mul_f32_e32 v213, 0x4f800000, v162
	v_cmp_gt_f32_e32 vcc, s63, v162
	s_nop 1
	v_cndmask_b32_e32 v162, v162, v213, vcc
	v_sqrt_f32_e32 v213, v162
	s_nop 0
	v_add_u32_e32 v216, -1, v213
	v_add_u32_e32 v217, 1, v213
	v_fma_f32 v218, -v216, v213, v162
	v_fma_f32 v219, -v217, v213, v162
	v_cmp_ge_f32_e64 s[60:61], 0, v218
	s_nop 1
	v_cndmask_b32_e64 v213, v213, v216, s[60:61]
	v_cmp_lt_f32_e64 s[60:61], 0, v219
	s_nop 1
	v_cndmask_b32_e64 v213, v213, v217, s[60:61]
	v_mul_f32_e32 v216, 0x37800000, v213
	v_cndmask_b32_e32 v213, v213, v216, vcc
	v_cmp_class_f32_e32 vcc, v162, v201
	s_nop 1
	v_cndmask_b32_e32 v162, v213, v162, vcc
	v_div_scale_f32 v216, s[60:61], v162, v162, 1.0
	v_rcp_f32_e32 v213, v216
	v_div_scale_f32 v217, vcc, 1.0, v162, 1.0
	v_fma_f32 v218, -v216, v213, 1.0
	v_fmac_f32_e32 v213, v218, v213
	v_mul_f32_e32 v218, v217, v213
	v_fma_f32 v219, -v216, v218, v217
	v_fmac_f32_e32 v218, v219, v213
	v_fma_f32 v216, -v216, v218, v217
	v_div_fmas_f32 v216, v216, v213, v218
	v_div_fixup_f32 v162, v216, v162, 1.0
	v_ffbh_u32_e32 v212, v135
	v_min_u32_e32 v212, 32, v212
	v_lshlrev_b64 v[214:215], v212, v[134:135]
	v_min_u32_e32 v214, 1, v214
	v_or_b32_e32 v214, v215, v214
	v_cvt_f32_u32_e32 v214, v214
	v_sub_u32_e32 v212, 32, v212
	v_ldexp_f32 v163, v214, v212
	v_fmamk_f32 v163, v163, 0x30800000, v200
	v_mul_f32_e32 v213, 0x4f800000, v163
	v_cmp_gt_f32_e32 vcc, s63, v163
	s_nop 1
	v_cndmask_b32_e32 v163, v163, v213, vcc
	v_sqrt_f32_e32 v213, v163
	s_nop 0
	v_add_u32_e32 v216, -1, v213
	v_add_u32_e32 v217, 1, v213
	v_fma_f32 v218, -v216, v213, v163
	v_fma_f32 v219, -v217, v213, v163
	v_cmp_ge_f32_e64 s[60:61], 0, v218
	s_nop 1
	v_cndmask_b32_e64 v213, v213, v216, s[60:61]
	v_cmp_lt_f32_e64 s[60:61], 0, v219
	s_nop 1
	v_cndmask_b32_e64 v213, v213, v217, s[60:61]
	v_mul_f32_e32 v216, 0x37800000, v213
	v_cndmask_b32_e32 v213, v213, v216, vcc
	v_cmp_class_f32_e32 vcc, v163, v201
	s_nop 1
	v_cndmask_b32_e32 v163, v213, v163, vcc
	v_div_scale_f32 v216, s[60:61], v163, v163, 1.0
	v_rcp_f32_e32 v213, v216
	v_div_scale_f32 v217, vcc, 1.0, v163, 1.0
	v_fma_f32 v218, -v216, v213, 1.0
	v_fmac_f32_e32 v213, v218, v213
	v_mul_f32_e32 v218, v217, v213
	v_fma_f32 v219, -v216, v218, v217
	v_fmac_f32_e32 v218, v219, v213
	v_fma_f32 v216, -v216, v218, v217
	v_div_fmas_f32 v216, v216, v213, v218
	v_div_fixup_f32 v163, v216, v163, 1.0
	v_ffbh_u32_e32 v212, v137
	v_min_u32_e32 v212, 32, v212
	v_lshlrev_b64 v[214:215], v212, v[136:137]
	v_min_u32_e32 v214, 1, v214
	v_or_b32_e32 v214, v215, v214
	v_cvt_f32_u32_e32 v214, v214
	v_sub_u32_e32 v212, 32, v212
	v_ldexp_f32 v164, v214, v212
	v_fmamk_f32 v164, v164, 0x30800000, v200
	v_mul_f32_e32 v213, 0x4f800000, v164
	v_cmp_gt_f32_e32 vcc, s63, v164
	s_nop 1
	v_cndmask_b32_e32 v164, v164, v213, vcc
	v_sqrt_f32_e32 v213, v164
	s_nop 0
	v_add_u32_e32 v216, -1, v213
	v_add_u32_e32 v217, 1, v213
	v_fma_f32 v218, -v216, v213, v164
	v_fma_f32 v219, -v217, v213, v164
	v_cmp_ge_f32_e64 s[60:61], 0, v218
	s_nop 1
	v_cndmask_b32_e64 v213, v213, v216, s[60:61]
	v_cmp_lt_f32_e64 s[60:61], 0, v219
	s_nop 1
	v_cndmask_b32_e64 v213, v213, v217, s[60:61]
	v_mul_f32_e32 v216, 0x37800000, v213
	v_cndmask_b32_e32 v213, v213, v216, vcc
	v_cmp_class_f32_e32 vcc, v164, v201
	s_nop 1
	v_cndmask_b32_e32 v164, v213, v164, vcc
	v_div_scale_f32 v216, s[60:61], v164, v164, 1.0
	v_rcp_f32_e32 v213, v216
	v_div_scale_f32 v217, vcc, 1.0, v164, 1.0
	v_fma_f32 v218, -v216, v213, 1.0
	v_fmac_f32_e32 v213, v218, v213
	v_mul_f32_e32 v218, v217, v213
	v_fma_f32 v219, -v216, v218, v217
	v_fmac_f32_e32 v218, v219, v213
	v_fma_f32 v216, -v216, v218, v217
	v_div_fmas_f32 v216, v216, v213, v218
	v_div_fixup_f32 v164, v216, v164, 1.0
	v_ffbh_u32_e32 v212, v139
	v_min_u32_e32 v212, 32, v212
	v_lshlrev_b64 v[214:215], v212, v[138:139]
	v_min_u32_e32 v214, 1, v214
; __global__ void __launch_bounds__(NTHR, 2) mega(Params p) {
;     ...
;             const float rs = 1.0f / sqrtf((float)ssF[r] * SSKI + EPSN); const f32x4 g0 = *(const f32x4*)(p.g_final + c), g1 = *(const f32x4*)(p.g_final + c + 4);
	v_or_b32_e32 v214, v215, v214
	v_cvt_f32_u32_e32 v214, v214
	v_sub_u32_e32 v212, 32, v212
	v_ldexp_f32 v165, v214, v212
	v_fmamk_f32 v165, v165, 0x30800000, v200
	v_mul_f32_e32 v213, 0x4f800000, v165
	v_cmp_gt_f32_e32 vcc, s63, v165
	s_nop 1
	v_cndmask_b32_e32 v165, v165, v213, vcc
	v_sqrt_f32_e32 v213, v165
	s_nop 0
	v_add_u32_e32 v216, -1, v213
	v_add_u32_e32 v217, 1, v213
	v_fma_f32 v218, -v216, v213, v165
	v_fma_f32 v219, -v217, v213, v165
	v_cmp_ge_f32_e64 s[60:61], 0, v218
	s_nop 1
	v_cndmask_b32_e64 v213, v213, v216, s[60:61]
	v_cmp_lt_f32_e64 s[60:61], 0, v219
	s_nop 1
	v_cndmask_b32_e64 v213, v213, v217, s[60:61]
	v_mul_f32_e32 v216, 0x37800000, v213
	v_cndmask_b32_e32 v213, v213, v216, vcc
	v_cmp_class_f32_e32 vcc, v165, v201
	s_nop 1
	v_cndmask_b32_e32 v165, v213, v165, vcc
	v_div_scale_f32 v216, s[60:61], v165, v165, 1.0
	v_rcp_f32_e32 v213, v216
	v_div_scale_f32 v217, vcc, 1.0, v165, 1.0
	v_fma_f32 v218, -v216, v213, 1.0
	v_fmac_f32_e32 v213, v218, v213
	v_mul_f32_e32 v218, v217, v213
	v_fma_f32 v219, -v216, v218, v217
	v_fmac_f32_e32 v218, v219, v213
	v_fma_f32 v216, -v216, v218, v217
	v_div_fmas_f32 v216, v216, v213, v218
	v_div_fixup_f32 v165, v216, v165, 1.0
	v_ffbh_u32_e32 v212, v141
	v_min_u32_e32 v212, 32, v212
	v_lshlrev_b64 v[214:215], v212, v[140:141]
	v_min_u32_e32 v214, 1, v214
	v_or_b32_e32 v214, v215, v214
	v_cvt_f32_u32_e32 v214, v214
	v_sub_u32_e32 v212, 32, v212
	v_ldexp_f32 v166, v214, v212
	v_fmamk_f32 v166, v166, 0x30800000, v200
	v_mul_f32_e32 v213, 0x4f800000, v166
	v_cmp_gt_f32_e32 vcc, s63, v166
	s_nop 1
	v_cndmask_b32_e32 v166, v166, v213, vcc
	v_sqrt_f32_e32 v213, v166
	s_nop 0
	v_add_u32_e32 v216, -1, v213
	v_add_u32_e32 v217, 1, v213
	v_fma_f32 v218, -v216, v213, v166
	v_fma_f32 v219, -v217, v213, v166
	v_cmp_ge_f32_e64 s[60:61], 0, v218
	s_nop 1
	v_cndmask_b32_e64 v213, v213, v216, s[60:61]
	v_cmp_lt_f32_e64 s[60:61], 0, v219
	s_nop 1
	v_cndmask_b32_e64 v213, v213, v217, s[60:61]
	v_mul_f32_e32 v216, 0x37800000, v213
	v_cndmask_b32_e32 v213, v213, v216, vcc
	v_cmp_class_f32_e32 vcc, v166, v201
	s_nop 1
	v_cndmask_b32_e32 v166, v213, v166, vcc
	v_div_scale_f32 v216, s[60:61], v166, v166, 1.0
	v_rcp_f32_e32 v213, v216
	v_div_scale_f32 v217, vcc, 1.0, v166, 1.0
	v_fma_f32 v218, -v216, v213, 1.0
	v_fmac_f32_e32 v213, v218, v213
	v_mul_f32_e32 v218, v217, v213
	v_fma_f32 v219, -v216, v218, v217
	v_fmac_f32_e32 v218, v219, v213
	v_fma_f32 v216, -v216, v218, v217
	v_div_fmas_f32 v216, v216, v213, v218
	v_div_fixup_f32 v166, v216, v166, 1.0
	v_ffbh_u32_e32 v212, v143
	v_min_u32_e32 v212, 32, v212
	v_lshlrev_b64 v[214:215], v212, v[142:143]
	v_min_u32_e32 v214, 1, v214
	v_or_b32_e32 v214, v215, v214
	v_cvt_f32_u32_e32 v214, v214
	v_sub_u32_e32 v212, 32, v212
	v_ldexp_f32 v167, v214, v212
	v_fmamk_f32 v167, v167, 0x30800000, v200
	v_mul_f32_e32 v213, 0x4f800000, v167
	v_cmp_gt_f32_e32 vcc, s63, v167
	s_nop 1
	v_cndmask_b32_e32 v167, v167, v213, vcc
	v_sqrt_f32_e32 v213, v167
	s_nop 0
	v_add_u32_e32 v216, -1, v213
	v_add_u32_e32 v217, 1, v213
	v_fma_f32 v218, -v216, v213, v167
	v_fma_f32 v219, -v217, v213, v167
	v_cmp_ge_f32_e64 s[60:61], 0, v218
	s_nop 1
	v_cndmask_b32_e64 v213, v213, v216, s[60:61]
	v_cmp_lt_f32_e64 s[60:61], 0, v219
	s_nop 1
	v_cndmask_b32_e64 v213, v213, v217, s[60:61]
	v_mul_f32_e32 v216, 0x37800000, v213
	v_cndmask_b32_e32 v213, v213, v216, vcc
	v_cmp_class_f32_e32 vcc, v167, v201
	s_nop 1
	v_cndmask_b32_e32 v167, v213, v167, vcc
	v_div_scale_f32 v216, s[60:61], v167, v167, 1.0
	v_rcp_f32_e32 v213, v216
	v_div_scale_f32 v217, vcc, 1.0, v167, 1.0
	v_fma_f32 v218, -v216, v213, 1.0
	v_fmac_f32_e32 v213, v218, v213
	v_mul_f32_e32 v218, v217, v213
	v_fma_f32 v219, -v216, v218, v217
	v_fmac_f32_e32 v218, v219, v213
	v_fma_f32 v216, -v216, v218, v217
	v_div_fmas_f32 v216, v216, v213, v218
	v_div_fixup_f32 v167, v216, v167, 1.0
	v_ffbh_u32_e32 v212, v145
	v_min_u32_e32 v212, 32, v212
	v_lshlrev_b64 v[214:215], v212, v[144:145]
	v_min_u32_e32 v214, 1, v214
	v_or_b32_e32 v214, v215, v214
	v_cvt_f32_u32_e32 v214, v214
	v_sub_u32_e32 v212, 32, v212
	v_ldexp_f32 v168, v214, v212
	v_fmamk_f32 v168, v168, 0x30800000, v200
	v_mul_f32_e32 v213, 0x4f800000, v168
	v_cmp_gt_f32_e32 vcc, s63, v168
	s_nop 1
	v_cndmask_b32_e32 v168, v168, v213, vcc
	v_sqrt_f32_e32 v213, v168
	s_nop 0
	v_add_u32_e32 v216, -1, v213
	v_add_u32_e32 v217, 1, v213
	v_fma_f32 v218, -v216, v213, v168
	v_fma_f32 v219, -v217, v213, v168
	v_cmp_ge_f32_e64 s[60:61], 0, v218
	s_nop 1
	v_cndmask_b32_e64 v213, v213, v216, s[60:61]
	v_cmp_lt_f32_e64 s[60:61], 0, v219
	s_nop 1
	v_cndmask_b32_e64 v213, v213, v217, s[60:61]
	v_mul_f32_e32 v216, 0x37800000, v213
	v_cndmask_b32_e32 v213, v213, v216, vcc
	v_cmp_class_f32_e32 vcc, v168, v201
	s_nop 1
	v_cndmask_b32_e32 v168, v213, v168, vcc
	v_div_scale_f32 v216, s[60:61], v168, v168, 1.0
	v_rcp_f32_e32 v213, v216
	v_div_scale_f32 v217, vcc, 1.0, v168, 1.0
	v_fma_f32 v218, -v216, v213, 1.0
	v_fmac_f32_e32 v213, v218, v213
	v_mul_f32_e32 v218, v217, v213
	v_fma_f32 v219, -v216, v218, v217
	v_fmac_f32_e32 v218, v219, v213
	v_fma_f32 v216, -v216, v218, v217
	v_div_fmas_f32 v216, v216, v213, v218
	v_div_fixup_f32 v168, v216, v168, 1.0
	v_ffbh_u32_e32 v212, v147
	v_min_u32_e32 v212, 32, v212
	v_lshlrev_b64 v[214:215], v212, v[146:147]
	v_min_u32_e32 v214, 1, v214
	v_or_b32_e32 v214, v215, v214
	v_cvt_f32_u32_e32 v214, v214
	v_sub_u32_e32 v212, 32, v212
	v_ldexp_f32 v169, v214, v212
	v_fmamk_f32 v169, v169, 0x30800000, v200
	v_mul_f32_e32 v213, 0x4f800000, v169
	v_cmp_gt_f32_e32 vcc, s63, v169
	s_nop 1
	v_cndmask_b32_e32 v169, v169, v213, vcc
	v_sqrt_f32_e32 v213, v169
	s_nop 0
	v_add_u32_e32 v216, -1, v213
; __global__ void __launch_bounds__(NTHR, 2) mega(Params p) {
;     ...
;             const float rs = 1.0f / sqrtf((float)ssF[r] * SSKI + EPSN); const f32x4 g0 = *(const f32x4*)(p.g_final + c), g1 = *(const f32x4*)(p.g_final + c + 4);
	v_add_u32_e32 v217, 1, v213
	v_fma_f32 v218, -v216, v213, v169
	v_fma_f32 v219, -v217, v213, v169
	v_cmp_ge_f32_e64 s[60:61], 0, v218
	s_nop 1
	v_cndmask_b32_e64 v213, v213, v216, s[60:61]
	v_cmp_lt_f32_e64 s[60:61], 0, v219
	s_nop 1
	v_cndmask_b32_e64 v213, v213, v217, s[60:61]
	v_mul_f32_e32 v216, 0x37800000, v213
	v_cndmask_b32_e32 v213, v213, v216, vcc
	v_cmp_class_f32_e32 vcc, v169, v201
	s_nop 1
	v_cndmask_b32_e32 v169, v213, v169, vcc
	v_div_scale_f32 v216, s[60:61], v169, v169, 1.0
	v_rcp_f32_e32 v213, v216
	v_div_scale_f32 v217, vcc, 1.0, v169, 1.0
	v_fma_f32 v218, -v216, v213, 1.0
	v_fmac_f32_e32 v213, v218, v213
	v_mul_f32_e32 v218, v217, v213
	v_fma_f32 v219, -v216, v218, v217
	v_fmac_f32_e32 v218, v219, v213
	v_fma_f32 v216, -v216, v218, v217
	v_div_fmas_f32 v216, v216, v213, v218
	v_div_fixup_f32 v169, v216, v169, 1.0
	v_ffbh_u32_e32 v212, v149
	v_min_u32_e32 v212, 32, v212
	v_lshlrev_b64 v[214:215], v212, v[148:149]
	v_min_u32_e32 v214, 1, v214
	v_or_b32_e32 v214, v215, v214
	v_cvt_f32_u32_e32 v214, v214
	v_sub_u32_e32 v212, 32, v212
	v_ldexp_f32 v170, v214, v212
	v_fmamk_f32 v170, v170, 0x30800000, v200
	v_mul_f32_e32 v213, 0x4f800000, v170
	v_cmp_gt_f32_e32 vcc, s63, v170
	s_nop 1
	v_cndmask_b32_e32 v170, v170, v213, vcc
	v_sqrt_f32_e32 v213, v170
	s_nop 0
	v_add_u32_e32 v216, -1, v213
	v_add_u32_e32 v217, 1, v213
	v_fma_f32 v218, -v216, v213, v170
	v_fma_f32 v219, -v217, v213, v170
	v_cmp_ge_f32_e64 s[60:61], 0, v218
	s_nop 1
	v_cndmask_b32_e64 v213, v213, v216, s[60:61]
	v_cmp_lt_f32_e64 s[60:61], 0, v219
	s_nop 1
	v_cndmask_b32_e64 v213, v213, v217, s[60:61]
	v_mul_f32_e32 v216, 0x37800000, v213
	v_cndmask_b32_e32 v213, v213, v216, vcc
	v_cmp_class_f32_e32 vcc, v170, v201
	s_nop 1
	v_cndmask_b32_e32 v170, v213, v170, vcc
	v_div_scale_f32 v216, s[60:61], v170, v170, 1.0
	v_rcp_f32_e32 v213, v216
	v_div_scale_f32 v217, vcc, 1.0, v170, 1.0
	v_fma_f32 v218, -v216, v213, 1.0
	v_fmac_f32_e32 v213, v218, v213
	v_mul_f32_e32 v218, v217, v213
	v_fma_f32 v219, -v216, v218, v217
	v_fmac_f32_e32 v218, v219, v213
	v_fma_f32 v216, -v216, v218, v217
	v_div_fmas_f32 v216, v216, v213, v218
	v_div_fixup_f32 v170, v216, v170, 1.0
	v_ffbh_u32_e32 v212, v151
	v_min_u32_e32 v212, 32, v212
	v_lshlrev_b64 v[214:215], v212, v[150:151]
	v_min_u32_e32 v214, 1, v214
	v_or_b32_e32 v214, v215, v214
	v_cvt_f32_u32_e32 v214, v214
	v_sub_u32_e32 v212, 32, v212
	v_ldexp_f32 v171, v214, v212
	v_fmamk_f32 v171, v171, 0x30800000, v200
	v_mul_f32_e32 v213, 0x4f800000, v171
	v_cmp_gt_f32_e32 vcc, s63, v171
	s_nop 1
	v_cndmask_b32_e32 v171, v171, v213, vcc
	v_sqrt_f32_e32 v213, v171
	s_nop 0
	v_add_u32_e32 v216, -1, v213
	v_add_u32_e32 v217, 1, v213
	v_fma_f32 v218, -v216, v213, v171
	v_fma_f32 v219, -v217, v213, v171
	v_cmp_ge_f32_e64 s[60:61], 0, v218
	s_nop 1
	v_cndmask_b32_e64 v213, v213, v216, s[60:61]
	v_cmp_lt_f32_e64 s[60:61], 0, v219
	s_nop 1
	v_cndmask_b32_e64 v213, v213, v217, s[60:61]
	v_mul_f32_e32 v216, 0x37800000, v213
	v_cndmask_b32_e32 v213, v213, v216, vcc
	v_cmp_class_f32_e32 vcc, v171, v201
	s_nop 1
	v_cndmask_b32_e32 v171, v213, v171, vcc
	v_div_scale_f32 v216, s[60:61], v171, v171, 1.0
	v_rcp_f32_e32 v213, v216
	v_div_scale_f32 v217, vcc, 1.0, v171, 1.0
	v_fma_f32 v218, -v216, v213, 1.0
	v_fmac_f32_e32 v213, v218, v213
	v_mul_f32_e32 v218, v217, v213
	v_fma_f32 v219, -v216, v218, v217
	v_fmac_f32_e32 v218, v219, v213
	v_fma_f32 v216, -v216, v218, v217
	v_div_fmas_f32 v216, v216, v213, v218
	v_div_fixup_f32 v171, v216, v171, 1.0
	v_ffbh_u32_e32 v212, v153
	v_min_u32_e32 v212, 32, v212
	v_lshlrev_b64 v[214:215], v212, v[152:153]
	v_min_u32_e32 v214, 1, v214
	v_or_b32_e32 v214, v215, v214
	v_cvt_f32_u32_e32 v214, v214
	v_sub_u32_e32 v212, 32, v212
	v_ldexp_f32 v172, v214, v212
	v_fmamk_f32 v172, v172, 0x30800000, v200
	v_mul_f32_e32 v213, 0x4f800000, v172
	v_cmp_gt_f32_e32 vcc, s63, v172
	s_nop 1
	v_cndmask_b32_e32 v172, v172, v213, vcc
	v_sqrt_f32_e32 v213, v172
	s_nop 0
	v_add_u32_e32 v216, -1, v213
	v_add_u32_e32 v217, 1, v213
	v_fma_f32 v218, -v216, v213, v172
	v_fma_f32 v219, -v217, v213, v172
	v_cmp_ge_f32_e64 s[60:61], 0, v218
	s_nop 1
	v_cndmask_b32_e64 v213, v213, v216, s[60:61]
	v_cmp_lt_f32_e64 s[60:61], 0, v219
	s_nop 1
	v_cndmask_b32_e64 v213, v213, v217, s[60:61]
	v_mul_f32_e32 v216, 0x37800000, v213
	v_cndmask_b32_e32 v213, v213, v216, vcc
	v_cmp_class_f32_e32 vcc, v172, v201
	s_nop 1
	v_cndmask_b32_e32 v172, v213, v172, vcc
; __global__ void __launch_bounds__(NTHR, 2) mega(Params p) {
;     ...
;             const float rs = 1.0f / sqrtf((float)ssF[r] * SSKI + EPSN); const f32x4 g0 = *(const f32x4*)(p.g_final + c), g1 = *(const f32x4*)(p.g_final + c + 4);
	v_div_scale_f32 v216, s[60:61], v172, v172, 1.0
	v_rcp_f32_e32 v213, v216
	v_div_scale_f32 v217, vcc, 1.0, v172, 1.0
	v_fma_f32 v218, -v216, v213, 1.0
	v_fmac_f32_e32 v213, v218, v213
	v_mul_f32_e32 v218, v217, v213
	v_fma_f32 v219, -v216, v218, v217
	v_fmac_f32_e32 v218, v219, v213
	v_fma_f32 v216, -v216, v218, v217
	v_div_fmas_f32 v216, v216, v213, v218
	v_div_fixup_f32 v172, v216, v172, 1.0
	v_ffbh_u32_e32 v212, v155
	v_min_u32_e32 v212, 32, v212
	v_lshlrev_b64 v[214:215], v212, v[154:155]
	v_min_u32_e32 v214, 1, v214
	v_or_b32_e32 v214, v215, v214
	v_cvt_f32_u32_e32 v214, v214
	v_sub_u32_e32 v212, 32, v212
	v_ldexp_f32 v173, v214, v212
	v_fmamk_f32 v173, v173, 0x30800000, v200
	v_mul_f32_e32 v213, 0x4f800000, v173
	v_cmp_gt_f32_e32 vcc, s63, v173
	s_nop 1
	v_cndmask_b32_e32 v173, v173, v213, vcc
	v_sqrt_f32_e32 v213, v173
	s_nop 0
	v_add_u32_e32 v216, -1, v213
	v_add_u32_e32 v217, 1, v213
	v_fma_f32 v218, -v216, v213, v173
	v_fma_f32 v219, -v217, v213, v173
	v_cmp_ge_f32_e64 s[60:61], 0, v218
	s_nop 1
	v_cndmask_b32_e64 v213, v213, v216, s[60:61]
	v_cmp_lt_f32_e64 s[60:61], 0, v219
	s_nop 1
	v_cndmask_b32_e64 v213, v213, v217, s[60:61]
	v_mul_f32_e32 v216, 0x37800000, v213
	v_cndmask_b32_e32 v213, v213, v216, vcc
	v_cmp_class_f32_e32 vcc, v173, v201
	s_nop 1
	v_cndmask_b32_e32 v173, v213, v173, vcc
	v_div_scale_f32 v216, s[60:61], v173, v173, 1.0
	v_rcp_f32_e32 v213, v216
	v_div_scale_f32 v217, vcc, 1.0, v173, 1.0
	v_fma_f32 v218, -v216, v213, 1.0
	v_fmac_f32_e32 v213, v218, v213
	v_mul_f32_e32 v218, v217, v213
	v_fma_f32 v219, -v216, v218, v217
	v_fmac_f32_e32 v218, v219, v213
	v_fma_f32 v216, -v216, v218, v217
	v_div_fmas_f32 v216, v216, v213, v218
	v_div_fixup_f32 v173, v216, v173, 1.0
	v_ffbh_u32_e32 v212, v157
	v_min_u32_e32 v212, 32, v212
	v_lshlrev_b64 v[214:215], v212, v[156:157]
	v_min_u32_e32 v214, 1, v214
	v_or_b32_e32 v214, v215, v214
	v_cvt_f32_u32_e32 v214, v214
	v_sub_u32_e32 v212, 32, v212
	v_ldexp_f32 v174, v214, v212
	v_fmamk_f32 v174, v174, 0x30800000, v200
	v_mul_f32_e32 v213, 0x4f800000, v174
	v_cmp_gt_f32_e32 vcc, s63, v174
	s_nop 1
	v_cndmask_b32_e32 v174, v174, v213, vcc
	v_sqrt_f32_e32 v213, v174
	s_nop 0
	v_add_u32_e32 v216, -1, v213
	v_add_u32_e32 v217, 1, v213
	v_fma_f32 v218, -v216, v213, v174
	v_fma_f32 v219, -v217, v213, v174
	v_cmp_ge_f32_e64 s[60:61], 0, v218
	s_nop 1
	v_cndmask_b32_e64 v213, v213, v216, s[60:61]
	v_cmp_lt_f32_e64 s[60:61], 0, v219
	s_nop 1
	v_cndmask_b32_e64 v213, v213, v217, s[60:61]
	v_mul_f32_e32 v216, 0x37800000, v213
	v_cndmask_b32_e32 v213, v213, v216, vcc
	v_cmp_class_f32_e32 vcc, v174, v201
	s_nop 1
	v_cndmask_b32_e32 v174, v213, v174, vcc
	v_div_scale_f32 v216, s[60:61], v174, v174, 1.0
	v_rcp_f32_e32 v213, v216
	v_div_scale_f32 v217, vcc, 1.0, v174, 1.0
	v_fma_f32 v218, -v216, v213, 1.0
	v_fmac_f32_e32 v213, v218, v213
	v_mul_f32_e32 v218, v217, v213
	v_fma_f32 v219, -v216, v218, v217
	v_fmac_f32_e32 v218, v219, v213
	v_fma_f32 v216, -v216, v218, v217
	v_div_fmas_f32 v216, v216, v213, v218
	v_div_fixup_f32 v174, v216, v174, 1.0
	v_ffbh_u32_e32 v212, v159
	v_min_u32_e32 v212, 32, v212
	v_lshlrev_b64 v[214:215], v212, v[158:159]
	v_min_u32_e32 v214, 1, v214
	v_or_b32_e32 v214, v215, v214
	v_cvt_f32_u32_e32 v214, v214
	v_sub_u32_e32 v212, 32, v212
	v_ldexp_f32 v175, v214, v212
	v_fmamk_f32 v175, v175, 0x30800000, v200
	v_mul_f32_e32 v213, 0x4f800000, v175
	v_cmp_gt_f32_e32 vcc, s63, v175
	s_nop 1
	v_cndmask_b32_e32 v175, v175, v213, vcc
	v_sqrt_f32_e32 v213, v175
	s_nop 0
	v_add_u32_e32 v216, -1, v213
	v_add_u32_e32 v217, 1, v213
	v_fma_f32 v218, -v216, v213, v175
	v_fma_f32 v219, -v217, v213, v175
	v_cmp_ge_f32_e64 s[60:61], 0, v218
	s_nop 1
	v_cndmask_b32_e64 v213, v213, v216, s[60:61]
	v_cmp_lt_f32_e64 s[60:61], 0, v219
	s_nop 1
	v_cndmask_b32_e64 v213, v213, v217, s[60:61]
	v_mul_f32_e32 v216, 0x37800000, v213
	v_cndmask_b32_e32 v213, v213, v216, vcc
	v_cmp_class_f32_e32 vcc, v175, v201
	s_nop 1
	v_cndmask_b32_e32 v175, v213, v175, vcc
	v_div_scale_f32 v216, s[60:61], v175, v175, 1.0
	v_rcp_f32_e32 v213, v216
	v_div_scale_f32 v217, vcc, 1.0, v175, 1.0
	v_fma_f32 v218, -v216, v213, 1.0
	v_fmac_f32_e32 v213, v218, v213
	v_mul_f32_e32 v218, v217, v213
	v_fma_f32 v219, -v216, v218, v217
	v_fmac_f32_e32 v218, v219, v213
	v_fma_f32 v216, -v216, v218, v217
	v_div_fmas_f32 v216, v216, v213, v218
	v_div_fixup_f32 v175, v216, v175, 1.0
	s_mov_b64 s[8:9], exec
	s_branch .LBB0_800

; __global__ void __launch_bounds__(NTHR, 2) mega(Params p) {
;     ...
;         for (size_t idx = (size_t)bid * NTHR + tid; idx < (size_t)16384 * DM / 8; idx += (size_t)G * NTHR) { const int r = (int)(idx >> 7), c = (int)(idx & 127) * 8;
;             const u32x4 q = *(const u32x4*)(xcp + (size_t)r * DM + c);
;             const float rs = 1.0f / sqrtf((float)ssF[r] * SSKI + EPSN); const f32x4 g0 = *(const f32x4*)(p.g_final + c), g1 = *(const f32x4*)(p.g_final + c + 4);
;             f32x4 v0 = {__uint_as_float(q.x << 16), __uint_as_float(q.x & 0xffff0000u), __uint_as_float(q.y << 16), __uint_as_float(q.y & 0xffff0000u)};
;             f32x4 v1 = {__uint_as_float(q.z << 16), __uint_as_float(q.z & 0xffff0000u), __uint_as_float(q.w << 16), __uint_as_float(q.w & 0xffff0000u)};
;             *(f32x4*)(p.out + (size_t)r * DM + c) = v0 * rs * g0; *(f32x4*)(p.out + (size_t)r * DM + c + 4) = v1 * rs * g1; } }
.LBB0_852:
	s_or_b64 exec, exec, s[4:5]
	s_waitcnt lgkmcnt(0)
	s_barrier
	s_cmpk_lg_u32 s34, 0x100
	s_cbranch_scc1 .Lfin_origB
	v_lshlrev_b32_e32 v204, 16, v64
	v_and_b32_e32 v205, 0xffff0000, v64
	v_lshlrev_b32_e32 v206, 16, v65
	v_and_b32_e32 v207, 0xffff0000, v65
	v_lshlrev_b32_e32 v208, 16, v66
	v_and_b32_e32 v209, 0xffff0000, v66
	v_lshlrev_b32_e32 v210, 16, v67
	v_and_b32_e32 v211, 0xffff0000, v67
	v_mov_b32_e32 v202, v160
	v_pk_mul_f32 v[204:205], v[202:203], v[204:205] op_sel_hi:[0,1]
	v_pk_mul_f32 v[206:207], v[202:203], v[206:207] op_sel_hi:[0,1]
	v_pk_mul_f32 v[208:209], v[202:203], v[208:209] op_sel_hi:[0,1]
	v_pk_mul_f32 v[210:211], v[202:203], v[210:211] op_sel_hi:[0,1]
	v_pk_mul_f32 v[204:205], v[36:37], v[204:205]
	v_pk_mul_f32 v[206:207], v[38:39], v[206:207]
	v_pk_mul_f32 v[208:209], v[40:41], v[208:209]
	v_pk_mul_f32 v[210:211], v[42:43], v[210:211]
	global_store_dwordx4 v33, v[204:207], s[40:41]
	global_store_dwordx4 v33, v[208:211], s[40:41] offset:16
	s_add_u32 s40, s40, 0x400000
	s_addc_u32 s41, s41, 0
	v_lshlrev_b32_e32 v204, 16, v68
	v_and_b32_e32 v205, 0xffff0000, v68
	v_lshlrev_b32_e32 v206, 16, v69
	v_and_b32_e32 v207, 0xffff0000, v69
	v_lshlrev_b32_e32 v208, 16, v70
	v_and_b32_e32 v209, 0xffff0000, v70
	v_lshlrev_b32_e32 v210, 16, v71
	v_and_b32_e32 v211, 0xffff0000, v71
	v_mov_b32_e32 v202, v161
	v_pk_mul_f32 v[204:205], v[202:203], v[204:205] op_sel_hi:[0,1]
	v_pk_mul_f32 v[206:207], v[202:203], v[206:207] op_sel_hi:[0,1]
	v_pk_mul_f32 v[208:209], v[202:203], v[208:209] op_sel_hi:[0,1]
	v_pk_mul_f32 v[210:211], v[202:203], v[210:211] op_sel_hi:[0,1]
	v_pk_mul_f32 v[204:205], v[36:37], v[204:205]
	v_pk_mul_f32 v[206:207], v[38:39], v[206:207]
	v_pk_mul_f32 v[208:209], v[40:41], v[208:209]
	v_pk_mul_f32 v[210:211], v[42:43], v[210:211]
	global_store_dwordx4 v33, v[204:207], s[40:41]
	global_store_dwordx4 v33, v[208:211], s[40:41] offset:16
	s_add_u32 s40, s40, 0x400000
	s_addc_u32 s41, s41, 0
	v_lshlrev_b32_e32 v204, 16, v72
	v_and_b32_e32 v205, 0xffff0000, v72
	v_lshlrev_b32_e32 v206, 16, v73
	v_and_b32_e32 v207, 0xffff0000, v73
	v_lshlrev_b32_e32 v208, 16, v74
	v_and_b32_e32 v209, 0xffff0000, v74
	v_lshlrev_b32_e32 v210, 16, v75
	v_and_b32_e32 v211, 0xffff0000, v75
	v_mov_b32_e32 v202, v162
	v_pk_mul_f32 v[204:205], v[202:203], v[204:205] op_sel_hi:[0,1]
	v_pk_mul_f32 v[206:207], v[202:203], v[206:207] op_sel_hi:[0,1]
	v_pk_mul_f32 v[208:209], v[202:203], v[208:209] op_sel_hi:[0,1]
	v_pk_mul_f32 v[210:211], v[202:203], v[210:211] op_sel_hi:[0,1]
	v_pk_mul_f32 v[204:205], v[36:37], v[204:205]
	v_pk_mul_f32 v[206:207], v[38:39], v[206:207]
	v_pk_mul_f32 v[208:209], v[40:41], v[208:209]
	v_pk_mul_f32 v[210:211], v[42:43], v[210:211]
	global_store_dwordx4 v33, v[204:207], s[40:41]
	global_store_dwordx4 v33, v[208:211], s[40:41] offset:16
	s_add_u32 s40, s40, 0x400000
	s_addc_u32 s41, s41, 0
	v_lshlrev_b32_e32 v204, 16, v76
	v_and_b32_e32 v205, 0xffff0000, v76
	v_lshlrev_b32_e32 v206, 16, v77
	v_and_b32_e32 v207, 0xffff0000, v77
	v_lshlrev_b32_e32 v208, 16, v78
	v_and_b32_e32 v209, 0xffff0000, v78
	v_lshlrev_b32_e32 v210, 16, v79
	v_and_b32_e32 v211, 0xffff0000, v79
	v_mov_b32_e32 v202, v163
	v_pk_mul_f32 v[204:205], v[202:203], v[204:205] op_sel_hi:[0,1]
	v_pk_mul_f32 v[206:207], v[202:203], v[206:207] op_sel_hi:[0,1]
	v_pk_mul_f32 v[208:209], v[202:203], v[208:209] op_sel_hi:[0,1]
	v_pk_mul_f32 v[210:211], v[202:203], v[210:211] op_sel_hi:[0,1]
	v_pk_mul_f32 v[204:205], v[36:37], v[204:205]
	v_pk_mul_f32 v[206:207], v[38:39], v[206:207]
	v_pk_mul_f32 v[208:209], v[40:41], v[208:209]
	v_pk_mul_f32 v[210:211], v[42:43], v[210:211]
	global_store_dwordx4 v33, v[204:207], s[40:41]
	global_store_dwordx4 v33, v[208:211], s[40:41] offset:16
	s_add_u32 s40, s40, 0x400000
	s_addc_u32 s41, s41, 0
	v_lshlrev_b32_e32 v204, 16, v80
	v_and_b32_e32 v205, 0xffff0000, v80
	v_lshlrev_b32_e32 v206, 16, v81
	v_and_b32_e32 v207, 0xffff0000, v81
	v_lshlrev_b32_e32 v208, 16, v82
	v_and_b32_e32 v209, 0xffff0000, v82
	v_lshlrev_b32_e32 v210, 16, v83
	v_and_b32_e32 v211, 0xffff0000, v83
	v_mov_b32_e32 v202, v164
	v_pk_mul_f32 v[204:205], v[202:203], v[204:205] op_sel_hi:[0,1]
	v_pk_mul_f32 v[206:207], v[202:203], v[206:207] op_sel_hi:[0,1]
	v_pk_mul_f32 v[208:209], v[202:203], v[208:209] op_sel_hi:[0,1]
	v_pk_mul_f32 v[210:211], v[202:203], v[210:211] op_sel_hi:[0,1]
	v_pk_mul_f32 v[204:205], v[36:37], v[204:205]
	v_pk_mul_f32 v[206:207], v[38:39], v[206:207]
	v_pk_mul_f32 v[208:209], v[40:41], v[208:209]
	v_pk_mul_f32 v[210:211], v[42:43], v[210:211]
	global_store_dwordx4 v33, v[204:207], s[40:41]
	global_store_dwordx4 v33, v[208:211], s[40:41] offset:16
	s_add_u32 s40, s40, 0x400000
	s_addc_u32 s41, s41, 0
	v_lshlrev_b32_e32 v204, 16, v84
	v_and_b32_e32 v205, 0xffff0000, v84
	v_lshlrev_b32_e32 v206, 16, v85
	v_and_b32_e32 v207, 0xffff0000, v85
	v_lshlrev_b32_e32 v208, 16, v86
	v_and_b32_e32 v209, 0xffff0000, v86
	v_lshlrev_b32_e32 v210, 16, v87
	v_and_b32_e32 v211, 0xffff0000, v87
	v_mov_b32_e32 v202, v165
	v_pk_mul_f32 v[204:205], v[202:203], v[204:205] op_sel_hi:[0,1]
	v_pk_mul_f32 v[206:207], v[202:203], v[206:207] op_sel_hi:[0,1]
	v_pk_mul_f32 v[208:209], v[202:203], v[208:209] op_sel_hi:[0,1]
	v_pk_mul_f32 v[210:211], v[202:203], v[210:211] op_sel_hi:[0,1]
	v_pk_mul_f32 v[204:205], v[36:37], v[204:205]
	v_pk_mul_f32 v[206:207], v[38:39], v[206:207]
	v_pk_mul_f32 v[208:209], v[40:41], v[208:209]
	v_pk_mul_f32 v[210:211], v[42:43], v[210:211]
	global_store_dwordx4 v33, v[204:207], s[40:41]
	global_store_dwordx4 v33, v[208:211], s[40:41] offset:16
	s_add_u32 s40, s40, 0x400000
	s_addc_u32 s41, s41, 0
	v_lshlrev_b32_e32 v204, 16, v88
; __global__ void __launch_bounds__(NTHR, 2) mega(Params p) {
;     ...
;         for (size_t idx = (size_t)bid * NTHR + tid; idx < (size_t)16384 * DM / 8; idx += (size_t)G * NTHR) { const int r = (int)(idx >> 7), c = (int)(idx & 127) * 8;
;             const u32x4 q = *(const u32x4*)(xcp + (size_t)r * DM + c);
;             const float rs = 1.0f / sqrtf((float)ssF[r] * SSKI + EPSN); const f32x4 g0 = *(const f32x4*)(p.g_final + c), g1 = *(const f32x4*)(p.g_final + c + 4);
;             f32x4 v0 = {__uint_as_float(q.x << 16), __uint_as_float(q.x & 0xffff0000u), __uint_as_float(q.y << 16), __uint_as_float(q.y & 0xffff0000u)};
;             f32x4 v1 = {__uint_as_float(q.z << 16), __uint_as_float(q.z & 0xffff0000u), __uint_as_float(q.w << 16), __uint_as_float(q.w & 0xffff0000u)};
;             *(f32x4*)(p.out + (size_t)r * DM + c) = v0 * rs * g0; *(f32x4*)(p.out + (size_t)r * DM + c + 4) = v1 * rs * g1; } }
	v_and_b32_e32 v205, 0xffff0000, v88
	v_lshlrev_b32_e32 v206, 16, v89
	v_and_b32_e32 v207, 0xffff0000, v89
	v_lshlrev_b32_e32 v208, 16, v90
	v_and_b32_e32 v209, 0xffff0000, v90
	v_lshlrev_b32_e32 v210, 16, v91
	v_and_b32_e32 v211, 0xffff0000, v91
	v_mov_b32_e32 v202, v166
	v_pk_mul_f32 v[204:205], v[202:203], v[204:205] op_sel_hi:[0,1]
	v_pk_mul_f32 v[206:207], v[202:203], v[206:207] op_sel_hi:[0,1]
	v_pk_mul_f32 v[208:209], v[202:203], v[208:209] op_sel_hi:[0,1]
	v_pk_mul_f32 v[210:211], v[202:203], v[210:211] op_sel_hi:[0,1]
	v_pk_mul_f32 v[204:205], v[36:37], v[204:205]
	v_pk_mul_f32 v[206:207], v[38:39], v[206:207]
	v_pk_mul_f32 v[208:209], v[40:41], v[208:209]
	v_pk_mul_f32 v[210:211], v[42:43], v[210:211]
	global_store_dwordx4 v33, v[204:207], s[40:41]
	global_store_dwordx4 v33, v[208:211], s[40:41] offset:16
	s_add_u32 s40, s40, 0x400000
	s_addc_u32 s41, s41, 0
	v_lshlrev_b32_e32 v204, 16, v92
	v_and_b32_e32 v205, 0xffff0000, v92
	v_lshlrev_b32_e32 v206, 16, v93
	v_and_b32_e32 v207, 0xffff0000, v93
	v_lshlrev_b32_e32 v208, 16, v94
	v_and_b32_e32 v209, 0xffff0000, v94
	v_lshlrev_b32_e32 v210, 16, v95
	v_and_b32_e32 v211, 0xffff0000, v95
	v_mov_b32_e32 v202, v167
	v_pk_mul_f32 v[204:205], v[202:203], v[204:205] op_sel_hi:[0,1]
	v_pk_mul_f32 v[206:207], v[202:203], v[206:207] op_sel_hi:[0,1]
	v_pk_mul_f32 v[208:209], v[202:203], v[208:209] op_sel_hi:[0,1]
	v_pk_mul_f32 v[210:211], v[202:203], v[210:211] op_sel_hi:[0,1]
	v_pk_mul_f32 v[204:205], v[36:37], v[204:205]
	v_pk_mul_f32 v[206:207], v[38:39], v[206:207]
	v_pk_mul_f32 v[208:209], v[40:41], v[208:209]
	v_pk_mul_f32 v[210:211], v[42:43], v[210:211]
	global_store_dwordx4 v33, v[204:207], s[40:41]
	global_store_dwordx4 v33, v[208:211], s[40:41] offset:16
	s_add_u32 s40, s40, 0x400000
	s_addc_u32 s41, s41, 0
	v_lshlrev_b32_e32 v204, 16, v96
	v_and_b32_e32 v205, 0xffff0000, v96
	v_lshlrev_b32_e32 v206, 16, v97
	v_and_b32_e32 v207, 0xffff0000, v97
	v_lshlrev_b32_e32 v208, 16, v98
	v_and_b32_e32 v209, 0xffff0000, v98
	v_lshlrev_b32_e32 v210, 16, v99
	v_and_b32_e32 v211, 0xffff0000, v99
	v_mov_b32_e32 v202, v168
	v_pk_mul_f32 v[204:205], v[202:203], v[204:205] op_sel_hi:[0,1]
	v_pk_mul_f32 v[206:207], v[202:203], v[206:207] op_sel_hi:[0,1]
	v_pk_mul_f32 v[208:209], v[202:203], v[208:209] op_sel_hi:[0,1]
	v_pk_mul_f32 v[210:211], v[202:203], v[210:211] op_sel_hi:[0,1]
	v_pk_mul_f32 v[204:205], v[36:37], v[204:205]
	v_pk_mul_f32 v[206:207], v[38:39], v[206:207]
	v_pk_mul_f32 v[208:209], v[40:41], v[208:209]
	v_pk_mul_f32 v[210:211], v[42:43], v[210:211]
	global_store_dwordx4 v33, v[204:207], s[40:41]
	global_store_dwordx4 v33, v[208:211], s[40:41] offset:16
	s_add_u32 s40, s40, 0x400000
	s_addc_u32 s41, s41, 0
	v_lshlrev_b32_e32 v204, 16, v100
	v_and_b32_e32 v205, 0xffff0000, v100
	v_lshlrev_b32_e32 v206, 16, v101
	v_and_b32_e32 v207, 0xffff0000, v101
	v_lshlrev_b32_e32 v208, 16, v102
	v_and_b32_e32 v209, 0xffff0000, v102
	v_lshlrev_b32_e32 v210, 16, v103
	v_and_b32_e32 v211, 0xffff0000, v103
	v_mov_b32_e32 v202, v169
	v_pk_mul_f32 v[204:205], v[202:203], v[204:205] op_sel_hi:[0,1]
	v_pk_mul_f32 v[206:207], v[202:203], v[206:207] op_sel_hi:[0,1]
	v_pk_mul_f32 v[208:209], v[202:203], v[208:209] op_sel_hi:[0,1]
	v_pk_mul_f32 v[210:211], v[202:203], v[210:211] op_sel_hi:[0,1]
	v_pk_mul_f32 v[204:205], v[36:37], v[204:205]
	v_pk_mul_f32 v[206:207], v[38:39], v[206:207]
	v_pk_mul_f32 v[208:209], v[40:41], v[208:209]
	v_pk_mul_f32 v[210:211], v[42:43], v[210:211]
	global_store_dwordx4 v33, v[204:207], s[40:41]
	global_store_dwordx4 v33, v[208:211], s[40:41] offset:16
	s_add_u32 s40, s40, 0x400000
	s_addc_u32 s41, s41, 0
	v_lshlrev_b32_e32 v204, 16, v104
	v_and_b32_e32 v205, 0xffff0000, v104
	v_lshlrev_b32_e32 v206, 16, v105
	v_and_b32_e32 v207, 0xffff0000, v105
	v_lshlrev_b32_e32 v208, 16, v106
	v_and_b32_e32 v209, 0xffff0000, v106
	v_lshlrev_b32_e32 v210, 16, v107
	v_and_b32_e32 v211, 0xffff0000, v107
	v_mov_b32_e32 v202, v170
	v_pk_mul_f32 v[204:205], v[202:203], v[204:205] op_sel_hi:[0,1]
	v_pk_mul_f32 v[206:207], v[202:203], v[206:207] op_sel_hi:[0,1]
	v_pk_mul_f32 v[208:209], v[202:203], v[208:209] op_sel_hi:[0,1]
	v_pk_mul_f32 v[210:211], v[202:203], v[210:211] op_sel_hi:[0,1]
	v_pk_mul_f32 v[204:205], v[36:37], v[204:205]
	v_pk_mul_f32 v[206:207], v[38:39], v[206:207]
	v_pk_mul_f32 v[208:209], v[40:41], v[208:209]
	v_pk_mul_f32 v[210:211], v[42:43], v[210:211]
	global_store_dwordx4 v33, v[204:207], s[40:41]
	global_store_dwordx4 v33, v[208:211], s[40:41] offset:16
	s_add_u32 s40, s40, 0x400000
	s_addc_u32 s41, s41, 0
	v_lshlrev_b32_e32 v204, 16, v108
	v_and_b32_e32 v205, 0xffff0000, v108
	v_lshlrev_b32_e32 v206, 16, v109
	v_and_b32_e32 v207, 0xffff0000, v109
	v_lshlrev_b32_e32 v208, 16, v110
; __global__ void __launch_bounds__(NTHR, 2) mega(Params p) {
;     ...
;         for (size_t idx = (size_t)bid * NTHR + tid; idx < (size_t)16384 * DM / 8; idx += (size_t)G * NTHR) { const int r = (int)(idx >> 7), c = (int)(idx & 127) * 8;
;             const u32x4 q = *(const u32x4*)(xcp + (size_t)r * DM + c);
;             const float rs = 1.0f / sqrtf((float)ssF[r] * SSKI + EPSN); const f32x4 g0 = *(const f32x4*)(p.g_final + c), g1 = *(const f32x4*)(p.g_final + c + 4);
;             f32x4 v0 = {__uint_as_float(q.x << 16), __uint_as_float(q.x & 0xffff0000u), __uint_as_float(q.y << 16), __uint_as_float(q.y & 0xffff0000u)};
;             f32x4 v1 = {__uint_as_float(q.z << 16), __uint_as_float(q.z & 0xffff0000u), __uint_as_float(q.w << 16), __uint_as_float(q.w & 0xffff0000u)};
;             *(f32x4*)(p.out + (size_t)r * DM + c) = v0 * rs * g0; *(f32x4*)(p.out + (size_t)r * DM + c + 4) = v1 * rs * g1; } }
	v_and_b32_e32 v209, 0xffff0000, v110
	v_lshlrev_b32_e32 v210, 16, v111
	v_and_b32_e32 v211, 0xffff0000, v111
	v_mov_b32_e32 v202, v171
	v_pk_mul_f32 v[204:205], v[202:203], v[204:205] op_sel_hi:[0,1]
	v_pk_mul_f32 v[206:207], v[202:203], v[206:207] op_sel_hi:[0,1]
	v_pk_mul_f32 v[208:209], v[202:203], v[208:209] op_sel_hi:[0,1]
	v_pk_mul_f32 v[210:211], v[202:203], v[210:211] op_sel_hi:[0,1]
	v_pk_mul_f32 v[204:205], v[36:37], v[204:205]
	v_pk_mul_f32 v[206:207], v[38:39], v[206:207]
	v_pk_mul_f32 v[208:209], v[40:41], v[208:209]
	v_pk_mul_f32 v[210:211], v[42:43], v[210:211]
	global_store_dwordx4 v33, v[204:207], s[40:41]
	global_store_dwordx4 v33, v[208:211], s[40:41] offset:16
	s_add_u32 s40, s40, 0x400000
	s_addc_u32 s41, s41, 0
	v_lshlrev_b32_e32 v204, 16, v112
	v_and_b32_e32 v205, 0xffff0000, v112
	v_lshlrev_b32_e32 v206, 16, v113
	v_and_b32_e32 v207, 0xffff0000, v113
	v_lshlrev_b32_e32 v208, 16, v114
	v_and_b32_e32 v209, 0xffff0000, v114
	v_lshlrev_b32_e32 v210, 16, v115
	v_and_b32_e32 v211, 0xffff0000, v115
	v_mov_b32_e32 v202, v172
	v_pk_mul_f32 v[204:205], v[202:203], v[204:205] op_sel_hi:[0,1]
	v_pk_mul_f32 v[206:207], v[202:203], v[206:207] op_sel_hi:[0,1]
	v_pk_mul_f32 v[208:209], v[202:203], v[208:209] op_sel_hi:[0,1]
	v_pk_mul_f32 v[210:211], v[202:203], v[210:211] op_sel_hi:[0,1]
	v_pk_mul_f32 v[204:205], v[36:37], v[204:205]
	v_pk_mul_f32 v[206:207], v[38:39], v[206:207]
	v_pk_mul_f32 v[208:209], v[40:41], v[208:209]
	v_pk_mul_f32 v[210:211], v[42:43], v[210:211]
	global_store_dwordx4 v33, v[204:207], s[40:41]
	global_store_dwordx4 v33, v[208:211], s[40:41] offset:16
	s_add_u32 s40, s40, 0x400000
	s_addc_u32 s41, s41, 0
	v_lshlrev_b32_e32 v204, 16, v116
	v_and_b32_e32 v205, 0xffff0000, v116
	v_lshlrev_b32_e32 v206, 16, v117
	v_and_b32_e32 v207, 0xffff0000, v117
	v_lshlrev_b32_e32 v208, 16, v118
	v_and_b32_e32 v209, 0xffff0000, v118
	v_lshlrev_b32_e32 v210, 16, v119
	v_and_b32_e32 v211, 0xffff0000, v119
	v_mov_b32_e32 v202, v173
	v_pk_mul_f32 v[204:205], v[202:203], v[204:205] op_sel_hi:[0,1]
	v_pk_mul_f32 v[206:207], v[202:203], v[206:207] op_sel_hi:[0,1]
	v_pk_mul_f32 v[208:209], v[202:203], v[208:209] op_sel_hi:[0,1]
	v_pk_mul_f32 v[210:211], v[202:203], v[210:211] op_sel_hi:[0,1]
	v_pk_mul_f32 v[204:205], v[36:37], v[204:205]
	v_pk_mul_f32 v[206:207], v[38:39], v[206:207]
	v_pk_mul_f32 v[208:209], v[40:41], v[208:209]
	v_pk_mul_f32 v[210:211], v[42:43], v[210:211]
	global_store_dwordx4 v33, v[204:207], s[40:41]
	global_store_dwordx4 v33, v[208:211], s[40:41] offset:16
	s_add_u32 s40, s40, 0x400000
	s_addc_u32 s41, s41, 0
	v_lshlrev_b32_e32 v204, 16, v120
	v_and_b32_e32 v205, 0xffff0000, v120
	v_lshlrev_b32_e32 v206, 16, v121
	v_and_b32_e32 v207, 0xffff0000, v121
	v_lshlrev_b32_e32 v208, 16, v122
	v_and_b32_e32 v209, 0xffff0000, v122
	v_lshlrev_b32_e32 v210, 16, v123
	v_and_b32_e32 v211, 0xffff0000, v123
	v_mov_b32_e32 v202, v174
	v_pk_mul_f32 v[204:205], v[202:203], v[204:205] op_sel_hi:[0,1]
	v_pk_mul_f32 v[206:207], v[202:203], v[206:207] op_sel_hi:[0,1]
	v_pk_mul_f32 v[208:209], v[202:203], v[208:209] op_sel_hi:[0,1]
	v_pk_mul_f32 v[210:211], v[202:203], v[210:211] op_sel_hi:[0,1]
	v_pk_mul_f32 v[204:205], v[36:37], v[204:205]
	v_pk_mul_f32 v[206:207], v[38:39], v[206:207]
	v_pk_mul_f32 v[208:209], v[40:41], v[208:209]
	v_pk_mul_f32 v[210:211], v[42:43], v[210:211]
	global_store_dwordx4 v33, v[204:207], s[40:41]
	global_store_dwordx4 v33, v[208:211], s[40:41] offset:16
	s_add_u32 s40, s40, 0x400000
	s_addc_u32 s41, s41, 0
	v_lshlrev_b32_e32 v204, 16, v124
	v_and_b32_e32 v205, 0xffff0000, v124
	v_lshlrev_b32_e32 v206, 16, v125
	v_and_b32_e32 v207, 0xffff0000, v125
	v_lshlrev_b32_e32 v208, 16, v126
	v_and_b32_e32 v209, 0xffff0000, v126
	v_lshlrev_b32_e32 v210, 16, v127
	v_and_b32_e32 v211, 0xffff0000, v127
	v_mov_b32_e32 v202, v175
	v_pk_mul_f32 v[204:205], v[202:203], v[204:205] op_sel_hi:[0,1]
	v_pk_mul_f32 v[206:207], v[202:203], v[206:207] op_sel_hi:[0,1]
	v_pk_mul_f32 v[208:209], v[202:203], v[208:209] op_sel_hi:[0,1]
	v_pk_mul_f32 v[210:211], v[202:203], v[210:211] op_sel_hi:[0,1]
	v_pk_mul_f32 v[204:205], v[36:37], v[204:205]
	v_pk_mul_f32 v[206:207], v[38:39], v[206:207]
	v_pk_mul_f32 v[208:209], v[40:41], v[208:209]
	v_pk_mul_f32 v[210:211], v[42:43], v[210:211]
	global_store_dwordx4 v33, v[204:207], s[40:41]
	global_store_dwordx4 v33, v[208:211], s[40:41] offset:16
	s_branch .LBB0_855
.Lfin_origB:
	s_and_saveexec_b64 s[4:5], s[0:1]
	s_cbranch_execz .LBB0_855
	s_lshl_b64 s[0:1], s[2:3], 12
	s_lshl_b64 s[4:5], s[34:35], 9
	v_lshl_add_u64 v[2:3], v[2:3], 3, s[0:1]
	s_lshl_b64 s[2:3], s[34:35], 12
	s_mov_b64 s[8:9], 0
	v_mov_b32_e32 v5, 0
	v_mov_b32_e32 v6, 0x358637bd
	s_mov_b32 s12, 0xf800000
	v_mov_b32_e32 v7, 0x260
	s_mov_b64 s[10:11], 0x1fffff
